# SSD phase: chunk B tile now lands in LDS by direct global->LDS loads (3-deep B ring, third buffer in a 24 KB static LDS extension) instead of VGPR staging + ds_write; B read addresses rebased per step
# speedup vs baseline: 1.0038x; 1.0021x over previous
; #define GAS __attribute__((address_space(1)))
; __device__ __forceinline__ void phase_ssd(const Params& P, int seg, unsigned char* smem) {
;     ...
;     const int tid = launder_v(threadIdx.x), lane = tid & 63, w = tid >> 6, fr = lane & 15, fq = lane >> 4;
;     const unsigned lds0 = (unsigned)(size_t)(LAS unsigned char*)smem;
;     bf16* StS = (bf16*)(smem + T_ST); float* acS = (float*)(smem + T_AC);
;     const int lt = w >> 1, pt = w & 1, tq = (lane & 15) >> 2, tp = lane & 3;
;     if (__builtin_amdgcn_readfirstlane(tid) >= 256) __builtin_amdgcn_s_setprio(1);
;     const int gx = grid_x();
;     for (int item = blockIdx.x; item < 256; item += gx) {
;         const int xcd = item & 7, ix = item >> 3, bg = xcd * 2 + (ix >> 4), b = bg >> 3, g = bg & 7, h = g * 8 + ((ix & 15) >> 1), ph = ix & 1;
;         const float Dh = P.d_skip[h];
;         const GAS float* stg = state + (size_t)(seg & 1) * (2 * 64 * 64 * 128) + ((size_t)(b * 64 + h) * 64 + ph * 32) * 128;
;         GAS float* stw = state + (size_t)((seg + 1) & 1) * (2 * 64 * 64 * 128) + ((size_t)(b * 64 + h) * 64 + ph * 32) * 128;
;         f32x4 st[2];
; #pragma unroll
;         for (int p2 = 0; p2 < 2; ++p2)
; #pragma unroll
;             for (int j = 0; j < 4; ++j) st[p2][j] = (seg == 0) ? 0.f : stg[(size_t)(p2 * 16 + fq * 4 + j) * 128 + w * 16 + fr];
;         __syncthreads();
; #pragma unroll
;         for (int p2 = 0; p2 < 2; ++p2)
; #pragma unroll
;             for (int j = 0; j < 4; ++j) StS[(p2 * 16 + fq * 4 + j) * 136 + w * 16 + fr] = (bf16)f2bf(st[p2][j]);
;         const int nchunks = TSEG / 64 + (seg == 0 ? 1 : 0);
;         struct Pre { v4u Br[2], Cr[2]; v2u Xr, Zr; float dtl, acl, alast, aclane; }; Pre RA, RB;
;         auto chunk_row0 = [&](int ci) -> int { return (seg == 0) ? (ci == 0 ? RS : b * TSEG + (ci - 1) * 64) : b * TSEG + ci * 64; };
;         auto load_chunk = [&](int ci, Pre& R) { const int row0 = chunk_row0(ci);
; #pragma unroll
;             for (int i = 0; i < 2; ++i) { const int q = tid + 512 * i, l = q >> 4, c8 = q & 15; const GAS bf16* rp = xconv + (size_t)(row0 + l) * DXBC + g * 128 + c8 * 8;
;                 R.Br[i] = *(const GAS v4u*)(rp + 4096); R.Cr[i] = *(const GAS v4u*)(rp + 5120); }
;             { const int l = tid >> 3, p4 = (tid & 7) * 4; R.Xr = *(const GAS v2u*)(xconv + (size_t)(row0 + l) * DXBC + h * 64 + ph * 32 + p4);
.LBB0_292:
	v_readlane_b32 s14, v253, 47
	v_readlane_b32 s15, v253, 48
	s_mov_b32 s9, s82
	s_andn2_b64 vcc, exec, s[14:15]
	v_cndmask_b32_e64 v4, 0, 1, s[14:15]
	v_cmp_ne_u32_e64 s[16:17], 1, v4
	s_nop 1
	v_writelane_b32 v255, s16, 7
	s_nop 1
	v_writelane_b32 v255, s17, 8
	s_cbranch_vccnz .LBB0_338
	s_mov_b64 exec, -1
	s_mov_b64 s[0:1], s[80:81]
	s_mov_b32 s63, s82
	v_readlane_b32 s24, v254, 38
	v_readlane_b32 s52, v252, 28
	v_readlane_b32 s53, v252, 29
	v_and_b32_e32 v156, 63, v172
	v_lshrrev_b32_e32 v157, 6, v172
	v_and_b32_e32 v158, 15, v172
	v_bfe_u32 v159, v172, 4, 2
	v_bfe_u32 v160, v172, 2, 2
	v_and_b32_e32 v161, 3, v172
	v_lshrrev_b32_e32 v162, 7, v172
	v_lshrrev_b32_e32 v163, 8, v172
	v_xor_b32_e32 v162, v162, v163
	v_bfe_u32 v163, v172, 6, 1
	v_readfirstlane_b32 s73, v157
	s_nop 3
	s_lshr_b32 s55, s73, 1
	s_lshr_b32 s65, s73, 2
	s_xor_b32 s55, s55, s65
	s_lshl_b32 s81, s73, 10
	v_lshrrev_b32_e32 v154, 4, v172
	v_and_b32_e32 v155, 7, v154
	v_lshlrev_b32_e32 v155, 1, v155
	v_xor_b32_e32 v155, v155, v158
	v_lshlrev_b32_e32 v155, 4, v155
	v_lshl_add_u32 v196, v154, 8, v155
	v_lshrrev_b32_e32 v155, 3, v172
	v_and_b32_e32 v164, 7, v172
	v_mul_u32_u24_e32 v198, 80, v155
	v_lshl_add_u32 v198, v164, 3, v198
	v_mul_u32_u24_e32 v200, 72, v155
	v_lshl_add_u32 v200, v164, 3, v200
	v_lshlrev_b32_e32 v202, 2, v155
	v_add_u32_e32 v202, 0x1d800, v202
	v_and_b32_e32 v165, 7, v158
	v_lshlrev_b32_e32 v165, 1, v165
	v_lshl_add_u32 v168, v163, 4, v158
	v_lshlrev_b32_e32 v168, 8, v168
	v_add_u32_e32 v168, 0x19800, v168
	v_add_u32_e32 v154, 0, v159
	v_xor_b32_e32 v154, v154, v165
	v_lshlrev_b32_e32 v154, 4, v154
	v_lshl_add_u32 v203, v158, 8, v154
	v_add_u32_e32 v211, v168, v154
	v_add_u32_e32 v154, 4, v159
	v_xor_b32_e32 v154, v154, v165
	v_lshlrev_b32_e32 v154, 4, v154
	v_lshl_add_u32 v204, v158, 8, v154
	v_add_u32_e32 v212, v168, v154
	v_add_u32_e32 v154, 8, v159
	v_xor_b32_e32 v154, v154, v165
	v_lshlrev_b32_e32 v154, 4, v154
	v_lshl_add_u32 v205, v158, 8, v154
	v_add_u32_e32 v213, v168, v154
	v_add_u32_e32 v154, 12, v159
	v_xor_b32_e32 v154, v154, v165
	v_lshlrev_b32_e32 v154, 4, v154
	v_lshl_add_u32 v206, v158, 8, v154
	v_add_u32_e32 v214, v168, v154
	v_lshlrev_b32_e32 v215, 2, v158
	v_add_u32_e32 v215, 0x1d800, v215
	v_lshlrev_b32_e32 v216, 4, v159
	v_add_u32_e32 v216, 0x1d800, v216
	v_lshl_add_u32 v154, v159, 2, v160
	v_mul_u32_u24_e32 v217, 80, v154
	v_lshl_add_u32 v217, v163, 5, v217
	v_lshl_add_u32 v217, v161, 3, v217
	v_mul_u32_u24_e32 v219, 72, v158
	v_lshl_add_u32 v219, v163, 5, v219
	v_lshl_add_u32 v219, v159, 3, v219
	v_mul_u32_u24_e32 v221, 80, v154
	v_lshl_add_u32 v221, v161, 3, v221
	v_and_b32_e32 v155, 7, v154
	v_lshlrev_b32_e32 v155, 1, v155
	v_lshrrev_b32_e32 v164, 1, v161
	v_and_b32_e32 v168, 1, v161
	v_lshlrev_b32_e32 v168, 3, v168
	v_lshl_add_u32 v168, v154, 8, v168
	v_and_b32_e32 v167, 3, v157
	v_lshl_add_u32 v165, v167, 2, v164
	v_xor_b32_e32 v165, v165, v155
	v_lshl_add_u32 v223, v165, 4, v168
	v_lshl_add_u32 v165, v167, 2, v164
	v_add_u32_e32 v165, 2, v165
	v_xor_b32_e32 v165, v165, v155
	v_lshl_add_u32 v224, v165, 4, v168
	v_and_b32_e32 v155, 7, v158
	v_lshlrev_b32_e32 v155, 1, v155
	v_lshrrev_b32_e32 v164, 1, v159
	v_and_b32_e32 v168, 1, v159
	v_lshlrev_b32_e32 v168, 3, v168
	v_lshl_add_u32 v168, v158, 8, v168
	v_add_u32_e32 v168, 0x19800, v168
	v_lshl_add_u32 v165, v167, 2, v164
	v_xor_b32_e32 v165, v165, v155
	v_lshl_add_u32 v227, v165, 4, v168
	v_lshl_add_u32 v165, v167, 2, v164
	v_add_u32_e32 v165, 2, v165
	v_xor_b32_e32 v165, v165, v155
	v_lshl_add_u32 v228, v165, 4, v168
	v_add_u32_e32 v197, 0xcc00, v196
	v_add_u32_e32 v199, 0xcc00, v198
	v_add_u32_e32 v201, 0xcc00, v200
	v_add_u32_e32 v218, 0xcc00, v217
	v_add_u32_e32 v220, 0xcc00, v219
	v_add_u32_e32 v222, 0xcc00, v221
	v_add_u32_e32 v207, 0xcc00, v203
	v_add_u32_e32 v208, 0xcc00, v204
	v_add_u32_e32 v209, 0xcc00, v205
	v_add_u32_e32 v210, 0xcc00, v206
	v_add_u32_e32 v225, 0xcc00, v223
	v_add_u32_e32 v226, 0xcc00, v224
	v_lshlrev_b32_e32 v154, 2, v159
	v_add_u32_e32 v155, 0, v154
	v_cmp_le_u32_e64 s[14:15], v155, v158
	v_add_u32_e32 v155, 1, v154
	v_cmp_le_u32_e64 s[16:17], v155, v158
	v_add_u32_e32 v155, 2, v154
	v_cmp_le_u32_e64 s[22:23], v155, v158
	v_add_u32_e32 v155, 3, v154
	v_cmp_le_u32_e64 s[34:35], v155, v158
	v_lshlrev_b32_e32 v195, 9, v158
	v_lshl_add_u32 v195, v167, 7, v195
	v_lshl_add_u32 v195, v159, 4, v195
	s_cmp_eq_u32 s24, 0
	s_cselect_b32 s60, 1, 0
	s_add_u32 s39, s60, 64
	s_mov_b32 s18, s2
; #define GAS __attribute__((address_space(1)))
; __device__ __forceinline__ void phase_ssd(const Params& P, int seg, unsigned char* smem) {
;     ...
;     for (int item = blockIdx.x; item < 256; item += gx) {
;         const int xcd = item & 7, ix = item >> 3, bg = xcd * 2 + (ix >> 4), b = bg >> 3, g = bg & 7, h = g * 8 + ((ix & 15) >> 1), ph = ix & 1;
;         const float Dh = P.d_skip[h];
;         const GAS float* stg = state + (size_t)(seg & 1) * (2 * 64 * 64 * 128) + ((size_t)(b * 64 + h) * 64 + ph * 32) * 128;
;         GAS float* stw = state + (size_t)((seg + 1) & 1) * (2 * 64 * 64 * 128) + ((size_t)(b * 64 + h) * 64 + ph * 32) * 128;
;         f32x4 st[2];
; #pragma unroll
;         for (int p2 = 0; p2 < 2; ++p2)
; #pragma unroll
;             for (int j = 0; j < 4; ++j) st[p2][j] = (seg == 0) ? 0.f : stg[(size_t)(p2 * 16 + fq * 4 + j) * 128 + w * 16 + fr];
;         __syncthreads();
; #pragma unroll
;         for (int p2 = 0; p2 < 2; ++p2)
; #pragma unroll
;             for (int j = 0; j < 4; ++j) StS[(p2 * 16 + fq * 4 + j) * 136 + w * 16 + fr] = (bf16)f2bf(st[p2][j]);
;         const int nchunks = TSEG / 64 + (seg == 0 ? 1 : 0);
;         struct Pre { v4u Br[2], Cr[2]; v2u Xr, Zr; float dtl, acl, alast, aclane; }; Pre RA, RB;
;         auto chunk_row0 = [&](int ci) -> int { return (seg == 0) ? (ci == 0 ? RS : b * TSEG + (ci - 1) * 64) : b * TSEG + ci * 64; };
;         auto load_chunk = [&](int ci, Pre& R) { const int row0 = chunk_row0(ci);
; #pragma unroll
;             for (int i = 0; i < 2; ++i) { const int q = tid + 512 * i, l = q >> 4, c8 = q & 15; const GAS bf16* rp = xconv + (size_t)(row0 + l) * DXBC + g * 128 + c8 * 8;
;                 R.Br[i] = *(const GAS v4u*)(rp + 4096); R.Cr[i] = *(const GAS v4u*)(rp + 5120); }
;             { const int l = tid >> 3, p4 = (tid & 7) * 4; R.Xr = *(const GAS v2u*)(xconv + (size_t)(row0 + l) * DXBC + h * 64 + ph * 32 + p4);
;               R.Zr = __builtin_nontemporal_load((const GAS v2u*)(proj + (size_t)(row0 + l) * NPROJ + OFF_Z + h * 64 + ph * 32 + p4));
;               R.dtl = dtv[(size_t)(row0 + l) * 64 + h]; R.acl = acv[(size_t)(row0 + l) * 64 + h]; }
;             R.alast = acv[(size_t)(row0 + 63) * 64 + h]; R.aclane = acv[(size_t)(row0 + lane) * 64 + h]; };
;         load_chunk(0, RA); if (nchunks > 1) load_chunk(1, RB);
.Lssd_item:
	v_and_b32_e32 v158, 15, v172
	v_bfe_u32 v159, v172, 4, 2
	v_lshrrev_b32_e32 v162, 7, v172
	v_lshrrev_b32_e32 v163, 8, v172
	v_xor_b32_e32 v162, v162, v163
	v_bfe_u32 v163, v172, 6, 1
	v_lshrrev_b32_e32 v154, 4, v172
	v_lshrrev_b32_e32 v155, 3, v172
	v_and_b32_e32 v164, 7, v172
	v_mul_u32_u24_e32 v170, 0x3000, v154
	v_lshl_add_u32 v170, v158, 4, v170
	v_add_u32_e32 v170, 0x2000, v170
	v_mul_u32_u24_e32 v156, 0x3000, v155
	v_lshl_add_u32 v156, v164, 3, v156
	v_mul_u32_u24_e32 v160, 0xa000, v155
	v_lshl_add_u32 v160, v164, 3, v160
	v_add_u32_e32 v160, 0x3000, v160
	v_lshlrev_b32_e32 v161, 8, v155
	v_and_b32_e32 v165, 63, v172
	v_lshlrev_b32_e32 v165, 8, v165
	v_lshl_add_u32 v168, v162, 4, v158
	v_lshlrev_b32_e32 v168, 13, v168
	v_lshl_add_u32 v168, v163, 5, v168
	v_lshl_add_u32 v168, v159, 3, v168
	s_and_b32 s65, s18, 7
	s_lshr_b32 s66, s18, 3
	s_lshr_b32 s67, s66, 4
	s_lshl_b32 s65, s65, 1
	s_add_u32 s65, s65, s67
	s_lshr_b32 s72, s65, 3
	s_and_b32 s70, s65, 7
	s_and_b32 s71, s66, 1
	s_bfe_u32 s67, s66, 0x30001
	s_lshl_b32 s69, s70, 3
	s_add_u32 s69, s69, s67
	s_lshl_b32 s20, s72, 12
	s_cmp_eq_u32 s60, 1
	s_cselect_b32 s57, 0x2000, s20
	s_lshl_b32 s65, s70, 8
	v_add_u32_e32 v169, s65, v170
	v_add_u32_e32 v170, 0x60000, v169
	v_and_b32_e32 v162, 7, v154
	v_lshlrev_b32_e32 v162, 1, v162
	v_xor_b32_e32 v162, v162, v158
	v_sub_u32_e32 v162, v162, v158
	v_lshl_add_u32 v235, v162, 4, v169
	v_add_u32_e32 v236, 0x60000, v235
	s_lshl_b32 s65, s69, 7
	s_lshl_b32 s66, s71, 6
	s_add_u32 s65, s65, s66
	v_add_u32_e32 v171, s65, v156
	v_add_u32_e32 v174, s65, v160
	v_add_u32_e32 v194, s65, v168
	s_lshl_b32 s66, s69, 2
	v_add_u32_e32 v192, s66, v161
	s_add_u32 s67, s66, 0x3f00
	v_mov_b32_e32 v193, s67
	s_load_dword s61, s[52:53], s66
	s_lshl_b32 s65, s72, 6
	s_add_u32 s65, s65, s69
	s_lshl_b32 s65, s65, 6
	s_lshl_b32 s66, s71, 5
	s_add_u32 s65, s65, s66
	s_lshl_b32 s65, s65, 9
	s_add_u32 s65, s65, 0x3aef9000
	s_and_b32 s66, s24, 1
	s_mul_i32 s67, s66, 0x400000
	s_xor_b32 s66, s66, 1
	s_mul_i32 s68, s66, 0x400000
	s_add_u32 s68, s68, s65
	s_add_u32 s50, s0, s68
	s_addc_u32 s51, s1, 0
	s_add_u32 s67, s67, s65
	s_add_u32 s48, s0, s67
	s_addc_u32 s49, s1, 0
	v_mov_b32_e32 v8, 0
	v_mov_b32_e32 v9, 0
	v_mov_b32_e32 v10, 0
	v_mov_b32_e32 v11, 0
	v_mov_b32_e32 v12, 0
	v_mov_b32_e32 v13, 0
	v_mov_b32_e32 v14, 0
	v_mov_b32_e32 v15, 0
	v_mov_b32_e32 v16, 0
	v_mov_b32_e32 v17, 0
	v_mov_b32_e32 v18, 0
	v_mov_b32_e32 v19, 0
	v_mov_b32_e32 v20, 0
	v_mov_b32_e32 v21, 0
	v_mov_b32_e32 v22, 0
	v_mov_b32_e32 v23, 0
	s_cmp_eq_u32 s60, 1
	s_cbranch_scc1 .Lssd_nostate
	s_cmp_ge_u32 s55, 2
	s_cbranch_scc1 .Lssd_nostate
	v_add_u32_e32 v157, 0x2000, v195
	global_load_dwordx4 v[8:11], v195, s[48:49]
	global_load_dwordx4 v[12:15], v157, s[48:49]
	global_load_dwordx4 v[16:19], v195, s[48:49] offset:64
	global_load_dwordx4 v[20:23], v157, s[48:49] offset:64
.Lssd_nostate:
	s_mov_b32 s54, 0
	s_mov_b32 s66, 0
	s_sub_u32 s65, s66, s60
	s_lshl_b32 s65, s65, 6
	s_add_u32 s65, s65, s20
	s_cmp_eq_u32 s66, 0
	s_cselect_b32 s56, s57, s65
	s_mul_i32 s65, s56, 0x3000
	s_add_u32 s65, s65, 0x29fe1000
	s_add_u32 s40, s0, s65
	s_addc_u32 s41, s1, 0
	s_mul_i32 s65, s56, 0xa000
	s_add_u32 s65, s65, 0x134e1000
	s_add_u32 s42, s0, s65
	s_addc_u32 s43, s1, 0
	s_mul_i32 s65, s56, 0x100
	s_add_u32 s65, s65, 0x302e1000
	s_add_u32 s44, s0, s65
	s_addc_u32 s45, s1, 0
	s_mul_i32 s65, s56, 0x100
	s_add_u32 s65, s65, 0x3b79e000
	s_add_u32 s46, s0, s65
	s_addc_u32 s47, s1, 0
	s_mov_b32 s77, 0x4000
	s_mov_b32 s78, 0x10c00
	s_mov_b32 s79, 0x21100
	global_load_dwordx4 v[132:135], v169, s[40:41] offset:2048
	global_load_dwordx4 v[136:139], v170, s[40:41] offset:2048
	s_add_u32 m0, s77, s81
	s_nop 0
	global_load_lds_dwordx4 v235, s[40:41]
	s_add_u32 m0, m0, 0x2000
	s_nop 0
	global_load_lds_dwordx4 v236, s[40:41]
	global_load_dwordx2 v[4:5], v171, s[40:41]
	global_load_dwordx2 v[36:37], v174, s[42:43] nt
	global_load_dword v6, v192, s[44:45]
	global_load_dword v116, v192, s[46:47]
	global_load_dword v117, v193, s[46:47]
	s_mov_b32 s66, 1
	s_sub_u32 s65, s66, s60
	s_lshl_b32 s65, s65, 6
	s_add_u32 s65, s65, s20
	s_cmp_eq_u32 s66, 0
	s_cselect_b32 s67, s57, s65
	s_mul_i32 s65, s67, 0x3000
	s_add_u32 s65, s65, 0x29fe1000
	s_add_u32 s40, s0, s65
	s_addc_u32 s41, s1, 0
	s_mul_i32 s65, s67, 0xa000
	s_add_u32 s65, s65, 0x134e1000
	s_add_u32 s42, s0, s65
	s_addc_u32 s43, s1, 0
	s_mul_i32 s65, s67, 0x100
	s_add_u32 s65, s65, 0x302e1000
	s_add_u32 s44, s0, s65
	s_addc_u32 s45, s1, 0
	s_mul_i32 s65, s67, 0x100
	s_add_u32 s65, s65, 0x3b79e000
	s_add_u32 s46, s0, s65
	s_addc_u32 s47, s1, 0
	global_load_dwordx4 v[140:143], v169, s[40:41] offset:2048
	global_load_dwordx4 v[144:147], v170, s[40:41] offset:2048
	s_add_u32 m0, s78, s81
	s_nop 0
	global_load_lds_dwordx4 v235, s[40:41]
	s_add_u32 m0, m0, 0x2000
	s_nop 0
	global_load_lds_dwordx4 v236, s[40:41]
	global_load_dwordx2 v[148:149], v171, s[40:41]
	global_load_dwordx2 v[150:151], v174, s[42:43] nt
	global_load_dword v118, v192, s[44:45]
	global_load_dword v152, v192, s[46:47]
	global_load_dword v153, v193, s[46:47]
	s_mov_b32 s66, 2
	s_sub_u32 s65, s66, s60
	s_lshl_b32 s65, s65, 6
	s_add_u32 s65, s65, s20
	s_cmp_eq_u32 s66, 0
	s_cselect_b32 s67, s57, s65
	s_mul_i32 s65, s67, 0x3000
	s_add_u32 s65, s65, 0x29fe1000
	s_add_u32 s40, s0, s65
	s_addc_u32 s41, s1, 0
	s_mul_i32 s65, s67, 0xa000
	s_add_u32 s65, s65, 0x134e1000
	s_add_u32 s42, s0, s65
	s_addc_u32 s43, s1, 0
	s_mul_i32 s65, s67, 0x100
	s_add_u32 s65, s65, 0x302e1000
	s_add_u32 s44, s0, s65
	s_addc_u32 s45, s1, 0
	s_mul_i32 s65, s67, 0x100
	s_add_u32 s65, s65, 0x3b79e000
	s_add_u32 s46, s0, s65
	s_addc_u32 s47, s1, 0
	s_waitcnt vmcnt(0)
	s_waitcnt lgkmcnt(0)
	s_barrier
	s_cmp_ge_u32 s55, 2
	s_cbranch_scc1 .Lssd_noimg
	v_cvt_pk_bf16_f32 v156, v8, v9
	v_cvt_pk_bf16_f32 v157, v10, v11
	v_cvt_pk_bf16_f32 v158, v12, v13
	v_cvt_pk_bf16_f32 v159, v14, v15
	v_cvt_pk_bf16_f32 v160, v16, v17
	v_cvt_pk_bf16_f32 v161, v18, v19
	v_cvt_pk_bf16_f32 v162, v20, v21
	v_cvt_pk_bf16_f32 v163, v22, v23
	ds_write_b64 v227, v[156:157]
	ds_write_b64 v227, v[158:159] offset:4096
	ds_write_b64 v228, v[160:161]
	ds_write_b64 v228, v[162:163] offset:4096
	s_waitcnt lgkmcnt(0)
; __device__ __forceinline__ unsigned cvt_pk_bf16(float lo, float hi) { unsigned r; asm volatile("v_cvt_pk_bf16_f32 %0, %1, %2" : "=v"(r) : "v"(lo), "v"(hi)); return r; }
; __device__ __forceinline__ void phase_ssd(const Params& P, int seg, unsigned char* smem) {
;     ...
;             { const float e2 = __expf(R.alast - R.acl);
; #pragma unroll
;               for (int i = 0; i < 2; ++i) { const int q = tid + 512 * i, l = q >> 4, c8 = q & 15; *(v4u*)(sb + T_CS + l * 272 + c8 * 16) = R.Cr[i]; *(v4u*)(sb + T_BS + l * 272 + c8 * 16) = R.Br[i]; }
;               const int l = tid >> 3, p4 = (tid & 7) * 4;
;               const float x0 = bflo(R.Xr.x) * R.dtl, x1 = bfhi(R.Xr.x) * R.dtl, x2 = bflo(R.Xr.y) * R.dtl, x3 = bfhi(R.Xr.y) * R.dtl;
;               v2u d; d.x = cvt_pk_bf16(x0, x1); d.y = cvt_pk_bf16(x2, x3); *(v2u*)(sb + T_XD + l * 80 + p4 * 2) = d;
;               v2u e; e.x = cvt_pk_bf16(x0 * e2, x1 * e2); e.y = cvt_pk_bf16(x2 * e2, x3 * e2); *(v2u*)(sb + T_XE + l * 80 + p4 * 2) = e;
;               *(v2u*)(sb + T_XS + l * 64 + p4 * 2) = R.Xr; *(v2u*)(sb + T_ZS + l * 64 + p4 * 2) = R.Zr;
;               if (w == 0) acP[lane] = R.aclane; }
;             BAR_LDS();
;             if (ci + 2 < nchunks) load_chunk(ci + 2, R);
;             bf16x8 cf[4];
; #pragma unroll
;             for (int k = 0; k < 4; ++k) cf[k] = *(const bf16x8*)(sb + T_CS + (lt * 16 + fr) * 272 + (k * 32 + fq * 8) * 2);
;             f32x4 yo = {0.f, 0.f, 0.f, 0.f};
; #pragma unroll
;             for (int k = 0; k < 4; ++k) { const bf16x8 bb = *(const bf16x8*)((const unsigned char*)StR + (pt * 16 + fr) * 272 + (k * 32 + fq * 8) * 2); yo = mfma16(cf[k], bb, yo); }
; { const f32x4 a4 = *(const f32x4*)(acP + lt * 16 + fq * 4);
; #pragma unroll
;               for (int j = 0; j < 4; ++j) yo[j] *= __expf(a4[j]); }
;             const float acl_fr = acP[lt * 16 + fr]; const int lrow = lt * 16 + fr;
; #pragma unroll
;             for (int t = 0; t < 2; ++t) {
;                 if (2 * t <= lt) {
;                     v2u xb0, xb1;
;                     { const unsigned a0 = lds0 + par * T_BUF + T_XD + (32 * t + 4 * fq + tq) * 80 + (pt * 16 + 4 * tp) * 2, a1 = a0 + 16 * 80; TR_ISSUE(xb0, a0); TR_ISSUE(xb1, a1); }
;                     float m[8];
;                     { f32x4 s0 = {0.f, 0.f, 0.f, 0.f}, s1 = {0.f, 0.f, 0.f, 0.f};
; #pragma unroll
.Lssd_noimg:
	ds_write_b128 v196, v[132:135]
	ds_write_b128 v196, v[136:139] offset:8192
	v_sub_f32_e32 v188, v117, v116
	v_mul_f32_e32 v188, 0x3fb8aa3b, v188
	v_exp_f32_e32 v188, v188
	v_lshlrev_b32_e32 v184, 16, v4
	v_and_b32_e32 v185, 0xffff0000, v4
	v_lshlrev_b32_e32 v186, 16, v5
	v_and_b32_e32 v187, 0xffff0000, v5
	v_mul_f32_e32 v184, v184, v6
	v_mul_f32_e32 v185, v185, v6
	v_mul_f32_e32 v186, v186, v6
	v_mul_f32_e32 v187, v187, v6
	v_cvt_pk_bf16_f32 v190, v184, v185
	v_cvt_pk_bf16_f32 v191, v186, v187
	ds_write_b64 v198, v[190:191] offset:32768
	v_mul_f32_e32 v184, v184, v188
	v_mul_f32_e32 v185, v185, v188
	v_mul_f32_e32 v186, v186, v188
	v_mul_f32_e32 v187, v187, v188
	v_cvt_pk_bf16_f32 v164, v184, v185
	v_cvt_pk_bf16_f32 v165, v186, v187
	ds_write_b64 v198, v[164:165] offset:37888
	ds_write_b64 v200, v[4:5] offset:43008
	ds_write_b64 v200, v[36:37] offset:47616
	v_mul_f32_e32 v189, 0x3fb8aa3b, v116
	ds_write_b32 v202, v189
	v_mul_f32_e32 v166, 0x3fb8aa3b, v117
	v_exp_f32_e32 v166, v166
	s_waitcnt lgkmcnt(0)
	s_barrier
	s_cmp_eq_u32 s55, 1
	s_cbranch_scc1 .Lssd_loop1
	s_cmp_eq_u32 s55, 2
	s_cbranch_scc1 .Lssd_loop2
	s_cmp_eq_u32 s55, 3
	s_cbranch_scc1 .Lssd_loop3
.Lssd_loop0:
	v_add_u32_e32 v229, s77, v203
	v_add_u32_e32 v230, s77, v204
	v_add_u32_e32 v231, s77, v205
	v_add_u32_e32 v232, s77, v206
	v_add_u32_e32 v233, s77, v223
	v_add_u32_e32 v234, s77, v224
	ds_read_b128 v[28:31], v203
	ds_read_b128 v[32:35], v204
	ds_read_b128 v[40:43], v205
	ds_read_b128 v[44:47], v206
	ds_read_b128 v[48:51], v211
	ds_read_b128 v[52:55], v212
	ds_read_b128 v[56:59], v213
	ds_read_b128 v[60:63], v214
	ds_read_b32 v167, v215
	ds_read_b64_tr_b16 v[96:97], v233
	ds_read_b64_tr_b16 v[98:99], v233 offset:4096
	ds_read_b64_tr_b16 v[100:101], v233 offset:8192
	ds_read_b64_tr_b16 v[102:103], v233 offset:12288
	ds_read_b64_tr_b16 v[104:105], v234
	ds_read_b64_tr_b16 v[106:107], v234 offset:4096
	s_waitcnt lgkmcnt(11)
	ds_read_b64_tr_b16 v[108:109], v234 offset:8192
	ds_read_b64_tr_b16 v[110:111], v234 offset:12288
	ds_read_b64_tr_b16 v[112:113], v221 offset:37888
	ds_read_b64_tr_b16 v[114:115], v221 offset:39168
	s_waitcnt lgkmcnt(11)
	ds_read_b64_tr_b16 v[124:125], v221 offset:37920
	ds_read_b64_tr_b16 v[126:127], v221 offset:39200
	ds_read_b64_tr_b16 v[120:121], v221 offset:40448
	ds_read_b64_tr_b16 v[122:123], v221 offset:41728
	global_load_dwordx4 v[132:135], v169, s[40:41] offset:2048
	s_waitcnt lgkmcnt(11)
	ds_read_b64_tr_b16 v[128:129], v221 offset:40480
	ds_read_b64_tr_b16 v[130:131], v221 offset:41760
	ds_read_b128 v[64:67], v229
	ds_read_b128 v[68:71], v230
	s_waitcnt lgkmcnt(11)
	ds_read_b128 v[72:75], v231
	global_load_dwordx4 v[136:139], v170, s[40:41] offset:2048
	ds_read_b128 v[76:79], v232
	v_mfma_f32_16x16x32_bf16 v[24:27], v[48:51], v[28:31], 0
	v_mfma_f32_16x16x32_bf16 v[24:27], v[52:55], v[32:35], v[24:27]
	v_mfma_f32_16x16x32_bf16 v[24:27], v[56:59], v[40:43], v[24:27]
	v_mfma_f32_16x16x32_bf16 v[24:27], v[60:63], v[44:47], v[24:27]
	ds_read_b64_tr_b16 v[56:57], v217 offset:32768
	s_add_u32 m0, s79, s81
	s_nop 0
	global_load_lds_dwordx4 v235, s[40:41]
	ds_read_b64_tr_b16 v[58:59], v217 offset:34048
	v_mul_f32_e32 v8, v8, v166
	v_mul_f32_e32 v9, v9, v166
	v_mul_f32_e32 v10, v10, v166
	v_mul_f32_e32 v11, v11, v166
	s_add_u32 m0, m0, 0x2000
	s_nop 0
	global_load_lds_dwordx4 v236, s[40:41]
	v_mul_f32_e32 v12, v12, v166
	v_mul_f32_e32 v13, v13, v166
	v_mul_f32_e32 v14, v14, v166
	v_mul_f32_e32 v15, v15, v166
	v_mul_f32_e32 v16, v16, v166
	v_mul_f32_e32 v17, v17, v166
	global_load_dwordx2 v[4:5], v171, s[40:41]
	v_mul_f32_e32 v18, v18, v166
	v_mul_f32_e32 v19, v19, v166
	v_mul_f32_e32 v20, v20, v166
	v_mul_f32_e32 v21, v21, v166
	v_mul_f32_e32 v22, v22, v166
	global_load_dwordx2 v[36:37], v174, s[42:43] nt
	v_mul_f32_e32 v23, v23, v166
	s_waitcnt lgkmcnt(12)
	v_mfma_f32_16x16x32_bf16 v[8:11], v[96:99], v[112:115], v[8:11]
	s_waitcnt lgkmcnt(10)
	v_mfma_f32_16x16x32_bf16 v[12:15], v[96:99], v[124:127], v[12:15]
	v_mfma_f32_16x16x32_bf16 v[16:19], v[104:107], v[112:115], v[16:19]
	v_mfma_f32_16x16x32_bf16 v[20:23], v[104:107], v[124:127], v[20:23]
	s_waitcnt lgkmcnt(8)
	v_mfma_f32_16x16x32_bf16 v[8:11], v[100:103], v[120:123], v[8:11]
	global_load_dword v6, v192, s[44:45]
	s_waitcnt lgkmcnt(6)
	v_mfma_f32_16x16x32_bf16 v[12:15], v[100:103], v[128:131], v[12:15]
	v_mfma_f32_16x16x32_bf16 v[16:19], v[108:111], v[120:123], v[16:19]
	v_mfma_f32_16x16x32_bf16 v[20:23], v[108:111], v[128:131], v[20:23]
	ds_read_b128 v[96:99], v216
	ds_read_b64 v[124:125], v219 offset:43008
	global_load_dword v116, v192, s[46:47]
	ds_read_b64 v[126:127], v219 offset:47616
	s_waitcnt lgkmcnt(8)
	v_mfma_f32_16x16x32_bf16 v[48:51], v[64:67], v[28:31], 0
	s_waitcnt lgkmcnt(7)
	v_mfma_f32_16x16x32_bf16 v[48:51], v[68:71], v[32:35], v[48:51]
	s_waitcnt lgkmcnt(6)
	v_mfma_f32_16x16x32_bf16 v[48:51], v[72:75], v[40:43], v[48:51]
	s_waitcnt lgkmcnt(5)
	v_mfma_f32_16x16x32_bf16 v[48:51], v[76:79], v[44:47], v[48:51]
	v_exp_f32_e32 v168, v167
	global_load_dword v117, v193, s[46:47]
	v_mul_f32_e32 v24, v24, v168
	v_mul_f32_e32 v25, v25, v168
	v_mul_f32_e32 v26, v26, v168
	v_mul_f32_e32 v27, v27, v168
	v_cvt_pk_bf16_f32 v156, v8, v9
	s_add_u32 s66, s54, 3
	s_cmp_lt_u32 s66, s39
	s_cselect_b32 s74, 0xc0000, 0
	s_cselect_b32 s75, 0x280000, 0
	s_cselect_b32 s76, 0x4000, 0
	s_add_u32 s40, s40, s74
	s_addc_u32 s41, s41, 0
	s_add_u32 s42, s42, s75
	s_addc_u32 s43, s43, 0
	s_add_u32 s44, s44, s76
	s_addc_u32 s45, s45, 0
	s_add_u32 s46, s46, s76
	s_addc_u32 s47, s47, 0
	v_cvt_pk_bf16_f32 v157, v10, v11
	v_cvt_pk_bf16_f32 v158, v12, v13
	s_waitcnt vmcnt(10)
; __device__ __forceinline__ bf16 f2bfh(float f) { return (bf16)(cvt_pk_bf16(f, f) & 0xffffu); }
; __device__ __forceinline__ void phase_ssd(const Params& P, int seg, unsigned char* smem) {
;     ...
;                       for (int j = 0; j < 4; ++j) { const int si0 = (2 * t) * 16 + fq * 4 + j, si1 = si0 + 16;
;                           const float e0 = s0[j] * __expf(fminf(acl_fr - a0[j], 0.f)), e1 = s1[j] * __expf(fminf(acl_fr - a1[j], 0.f));
;                           m[j] = (si0 <= lrow) ? e0 : 0.f; m[4 + j] = (si1 <= lrow) ? e1 : 0.f; } }
;                     v4u mp; mp.x = cvt_pk_bf16(m[0], m[1]); mp.y = cvt_pk_bf16(m[2], m[3]); mp.z = cvt_pk_bf16(m[4], m[5]); mp.w = cvt_pk_bf16(m[6], m[7]);
;                     asm volatile("s_waitcnt lgkmcnt(0)" : "+v"(xb0), "+v"(xb1) :: "memory");
;                     yo = mfma16(__builtin_bit_cast(bf16x8, mp), mk8(xb0, xb1), yo);
;                 }
;             }
; #pragma unroll
;             for (int j = 0; j < 4; ++j) { const int l = lt * 16 + fq * 4 + j, p = pt * 16 + fr; const float xv = bf2f(*(const bf16*)(sb + T_XS + l * 64 + p * 2)), zv = bf2f(*(const bf16*)(sb + T_ZS + l * 64 + p * 2));
;                 ypre[(size_t)(row0 + l) * DINNER + h * 64 + ph * 32 + p] = f2bfh((yo[j] + Dh * xv) * siluf_(zv)); }
;             { v2u xa[2][2][2], bb[2][2];
; #pragma unroll
;               for (int kk = 0; kk < 2; ++kk) {
; #pragma unroll
;                   for (int hh = 0; hh < 2; ++hh) { const int r = kk * 32 + 8 * fq + 4 * hh + tq;
;                       TR_ISSUE(bb[kk][hh], lds0 + par * T_BUF + T_BS + r * 272 + (w * 16 + 4 * tp) * 2);
; #pragma unroll
;                       for (int p2 = 0; p2 < 2; ++p2) TR_ISSUE(xa[p2][kk][hh], lds0 + par * T_BUF + T_XE + r * 80 + (p2 * 16 + 4 * tp) * 2); } }
;               asm volatile("s_waitcnt lgkmcnt(0)" : "+v"(xa[0][0][0]), "+v"(xa[0][0][1]), "+v"(xa[0][1][0]), "+v"(xa[0][1][1]), "+v"(xa[1][0][0]), "+v"(xa[1][0][1]), "+v"(xa[1][1][0]), "+v"(xa[1][1][1]),
;                            "+v"(bb[0][0]), "+v"(bb[0][1]), "+v"(bb[1][0]), "+v"(bb[1][1]) :: "memory");
; #pragma unroll
;               for (int p2 = 0; p2 < 2; ++p2) { st[p2] *= dec;
; #pragma unroll
;                   for (int kk = 0; kk < 2; ++kk) st[p2] = mfma16(mk8(xa[p2][kk][0], xa[p2][kk][1]), mk8(bb[kk][0], bb[kk][1]), st[p2]); } }
; #pragma unroll
;             for (int p2 = 0; p2 < 2; ++p2)
; #pragma unroll
	v_cvt_pk_bf16_f32 v159, v14, v15
	v_cvt_pk_bf16_f32 v160, v16, v17
	ds_write_b128 v197, v[140:143]
	v_cvt_pk_bf16_f32 v161, v18, v19
	v_cvt_pk_bf16_f32 v162, v20, v21
	ds_write_b128 v197, v[144:147] offset:8192
	v_cvt_pk_bf16_f32 v163, v22, v23
	ds_write_b64 v227, v[156:157] offset:8192
	v_sub_f32_e32 v188, v153, v152
	ds_write_b64 v227, v[158:159] offset:12288
	ds_write_b64 v228, v[160:161] offset:8192
	v_mul_f32_e32 v188, 0x3fb8aa3b, v188
	ds_write_b64 v228, v[162:163] offset:12288
	v_exp_f32_e32 v188, v188
	s_waitcnt lgkmcnt(6)
	v_lshlrev_b32_e32 v112, 16, v126
	v_and_b32_e32 v113, 0xffff0000, v126
	v_lshlrev_b32_e32 v184, 16, v148
	v_lshlrev_b32_e32 v114, 16, v127
	v_and_b32_e32 v115, 0xffff0000, v127
	v_and_b32_e32 v185, 0xffff0000, v148
	v_mul_f32_e32 v120, 0xbfb8aa3b, v112
	v_mul_f32_e32 v121, 0xbfb8aa3b, v113
	v_lshlrev_b32_e32 v186, 16, v149
	v_mul_f32_e32 v122, 0xbfb8aa3b, v114
	v_mul_f32_e32 v123, 0xbfb8aa3b, v115
	v_and_b32_e32 v187, 0xffff0000, v149
	v_exp_f32_e32 v120, v120
	v_exp_f32_e32 v121, v121
	v_mul_f32_e32 v184, v184, v118
	v_exp_f32_e32 v122, v122
	v_mul_f32_e32 v185, v185, v118
	v_exp_f32_e32 v123, v123
	v_add_f32_e32 v120, 1.0, v120
	v_mul_f32_e32 v186, v186, v118
	v_add_f32_e32 v121, 1.0, v121
	v_add_f32_e32 v122, 1.0, v122
	v_mul_f32_e32 v187, v187, v118
	v_add_f32_e32 v123, 1.0, v123
	v_rcp_f32_e32 v120, v120
	v_cvt_pk_bf16_f32 v190, v184, v185
	v_rcp_f32_e32 v121, v121
	v_rcp_f32_e32 v122, v122
	v_cvt_pk_bf16_f32 v191, v186, v187
	v_rcp_f32_e32 v123, v123
	v_mul_f32_e32 v112, v120, v112
	ds_write_b64 v199, v[190:191] offset:32768
	v_mul_f32_e32 v113, v121, v113
	v_mul_f32_e32 v114, v122, v114
	v_mul_f32_e32 v184, v184, v188
	v_mul_f32_e32 v115, v123, v115
	v_mul_f32_e32 v185, v185, v188
	v_lshlrev_b32_e32 v120, 16, v124
	v_and_b32_e32 v121, 0xffff0000, v124
	v_mul_f32_e32 v186, v186, v188
	v_lshlrev_b32_e32 v122, 16, v125
	v_and_b32_e32 v123, 0xffff0000, v125
	v_mul_f32_e32 v187, v187, v188
	v_sub_f32_e32 v156, v167, v96
	v_sub_f32_e32 v157, v167, v97
	v_cvt_pk_bf16_f32 v164, v184, v185
	v_sub_f32_e32 v158, v167, v98
	v_sub_f32_e32 v159, v167, v99
	v_cvt_pk_bf16_f32 v165, v186, v187
	v_exp_f32_e32 v156, v156
	v_exp_f32_e32 v157, v157
	ds_write_b64 v199, v[164:165] offset:37888
	v_exp_f32_e32 v158, v158
	ds_write_b64 v201, v[148:149] offset:43008
	v_exp_f32_e32 v159, v159
	v_mul_f32_e32 v156, v48, v156
	ds_write_b64 v201, v[150:151] offset:47616
	v_mul_f32_e32 v157, v49, v157
	v_mul_f32_e32 v158, v50, v158
	v_mul_f32_e32 v189, 0x3fb8aa3b, v152
	v_mul_f32_e32 v159, v51, v159
	v_cndmask_b32_e64 v156, 0, v156, s[14:15]
	ds_write_b32 v202, v189 offset:256
	v_cndmask_b32_e64 v157, 0, v157, s[16:17]
	v_cndmask_b32_e64 v158, 0, v158, s[22:23]
	v_mul_f32_e32 v166, 0x3fb8aa3b, v153
	v_cndmask_b32_e64 v159, 0, v159, s[34:35]
	v_cvt_pk_bf16_f32 v128, v156, v157
	v_exp_f32_e32 v166, v166
	v_cvt_pk_bf16_f32 v129, v158, v159
	v_mov_b32_e32 v130, 0
	v_mov_b32_e32 v131, 0
	s_nop 1
	v_mfma_f32_16x16x32_bf16 v[24:27], v[56:59], v[128:131], v[24:27]
	s_mul_i32 s65, s56, 0x2000
	s_add_u32 s65, s65, 0x304f1000
	s_add_u32 s48, s0, s65
	s_addc_u32 s49, s1, 0
	s_nop 3
	v_fma_f32 v156, s61, v120, v24
	v_fma_f32 v157, s61, v121, v25
	v_fma_f32 v158, s61, v122, v26
	v_fma_f32 v159, s61, v123, v27
	v_mul_f32_e32 v156, v156, v112
	v_mul_f32_e32 v157, v157, v113
	v_mul_f32_e32 v158, v158, v114
	v_mul_f32_e32 v159, v159, v115
	v_cvt_pk_bf16_f32 v154, v156, v157
	v_cvt_pk_bf16_f32 v155, v158, v159
	global_store_dwordx2 v194, v[154:155], s[48:49]
	s_add_u32 s65, s54, 1
	s_sub_u32 s65, s65, s60
	s_lshl_b32 s65, s65, 6
	s_add_u32 s56, s65, s20
	s_waitcnt lgkmcnt(0)
	s_barrier
	s_mov_b32 s80, s77
	s_mov_b32 s77, s78
	s_mov_b32 s78, s79
	s_mov_b32 s79, s80
	s_add_u32 s54, s54, 1
	s_cmp_ge_u32 s54, s39
	s_cbranch_scc1 .Lssd_done
	v_add_u32_e32 v229, s77, v203
	v_add_u32_e32 v230, s77, v204
	v_add_u32_e32 v231, s77, v205
	v_add_u32_e32 v232, s77, v206
	v_add_u32_e32 v233, s77, v223
	v_add_u32_e32 v234, s77, v224
	ds_read_b128 v[28:31], v207
	ds_read_b128 v[32:35], v208
	ds_read_b128 v[40:43], v209
	ds_read_b128 v[44:47], v210
	ds_read_b128 v[48:51], v211 offset:8192
	ds_read_b128 v[52:55], v212 offset:8192
	ds_read_b128 v[56:59], v213 offset:8192
	ds_read_b128 v[60:63], v214 offset:8192
	ds_read_b32 v167, v215 offset:256
	ds_read_b64_tr_b16 v[96:97], v233
	ds_read_b64_tr_b16 v[98:99], v233 offset:4096
	ds_read_b64_tr_b16 v[100:101], v233 offset:8192
	ds_read_b64_tr_b16 v[102:103], v233 offset:12288
	ds_read_b64_tr_b16 v[104:105], v234
	ds_read_b64_tr_b16 v[106:107], v234 offset:4096
	s_waitcnt lgkmcnt(11)
	ds_read_b64_tr_b16 v[108:109], v234 offset:8192
	ds_read_b64_tr_b16 v[110:111], v234 offset:12288
	ds_read_b64_tr_b16 v[112:113], v222 offset:37888
	ds_read_b64_tr_b16 v[114:115], v222 offset:39168
	s_waitcnt lgkmcnt(11)
	ds_read_b64_tr_b16 v[124:125], v222 offset:37920
	ds_read_b64_tr_b16 v[126:127], v222 offset:39200
	ds_read_b64_tr_b16 v[120:121], v222 offset:40448
	ds_read_b64_tr_b16 v[122:123], v222 offset:41728
	global_load_dwordx4 v[140:143], v169, s[40:41] offset:2048
	s_waitcnt lgkmcnt(11)
	ds_read_b64_tr_b16 v[128:129], v222 offset:40480
	ds_read_b64_tr_b16 v[130:131], v222 offset:41760
	ds_read_b128 v[64:67], v229
	ds_read_b128 v[68:71], v230
	s_waitcnt lgkmcnt(11)
; __device__ __forceinline__ void phase_ssd(const Params& P, int seg, unsigned char* smem) {
;     ...
;             bf16x8 cf[4];
; #pragma unroll
;             for (int k = 0; k < 4; ++k) cf[k] = *(const bf16x8*)(sb + T_CS + (lt * 16 + fr) * 272 + (k * 32 + fq * 8) * 2);
;             f32x4 yo = {0.f, 0.f, 0.f, 0.f};
; #pragma unroll
;             for (int k = 0; k < 4; ++k) { const bf16x8 bb = *(const bf16x8*)((const unsigned char*)StR + (pt * 16 + fr) * 272 + (k * 32 + fq * 8) * 2); yo = mfma16(cf[k], bb, yo); }
; { const f32x4 a4 = *(const f32x4*)(acP + lt * 16 + fq * 4);
; #pragma unroll
;               for (int j = 0; j < 4; ++j) yo[j] *= __expf(a4[j]); }
;             const float acl_fr = acP[lt * 16 + fr]; const int lrow = lt * 16 + fr;
; #pragma unroll
;             for (int t = 0; t < 2; ++t) {
;                 if (2 * t <= lt) {
;                     v2u xb0, xb1;
;                     { const unsigned a0 = lds0 + par * T_BUF + T_XD + (32 * t + 4 * fq + tq) * 80 + (pt * 16 + 4 * tp) * 2, a1 = a0 + 16 * 80; TR_ISSUE(xb0, a0); TR_ISSUE(xb1, a1); }
;                     float m[8];
;                     { f32x4 s0 = {0.f, 0.f, 0.f, 0.f}, s1 = {0.f, 0.f, 0.f, 0.f};
; #pragma unroll
;                       for (int k = 0; k < 4; ++k) { const bf16x8 bf0 = *(const bf16x8*)(sb + T_BS + ((2 * t) * 16 + fr) * 272 + (k * 32 + fq * 8) * 2), bf1 = *(const bf16x8*)(sb + T_BS + ((2 * t + 1) * 16 + fr) * 272 + (k * 32 + fq * 8) * 2);
;                           s0 = mfma16(bf0, cf[k], s0); s1 = mfma16(bf1, cf[k], s1); }
;                       const f32x4 a0 = *(const f32x4*)(acP + (2 * t) * 16 + fq * 4), a1 = *(const f32x4*)(acP + (2 * t + 1) * 16 + fq * 4);
; #pragma unroll
;                       for (int j = 0; j < 4; ++j) { const int si0 = (2 * t) * 16 + fq * 4 + j, si1 = si0 + 16;
;                           const float e0 = s0[j] * __expf(fminf(acl_fr - a0[j], 0.f)), e1 = s1[j] * __expf(fminf(acl_fr - a1[j], 0.f));
;                           m[j] = (si0 <= lrow) ? e0 : 0.f; m[4 + j] = (si1 <= lrow) ? e1 : 0.f; } }
;                     v4u mp; mp.x = cvt_pk_bf16(m[0], m[1]); mp.y = cvt_pk_bf16(m[2], m[3]); mp.z = cvt_pk_bf16(m[4], m[5]); mp.w = cvt_pk_bf16(m[6], m[7]);
;                     asm volatile("s_waitcnt lgkmcnt(0)" : "+v"(xb0), "+v"(xb1) :: "memory");
;                     yo = mfma16(__builtin_bit_cast(bf16x8, mp), mk8(xb0, xb1), yo);
	ds_read_b128 v[72:75], v231
	global_load_dwordx4 v[144:147], v170, s[40:41] offset:2048
	ds_read_b128 v[76:79], v232
	v_mfma_f32_16x16x32_bf16 v[24:27], v[48:51], v[28:31], 0
	v_mfma_f32_16x16x32_bf16 v[24:27], v[52:55], v[32:35], v[24:27]
	v_mfma_f32_16x16x32_bf16 v[24:27], v[56:59], v[40:43], v[24:27]
	v_mfma_f32_16x16x32_bf16 v[24:27], v[60:63], v[44:47], v[24:27]
	ds_read_b64_tr_b16 v[56:57], v218 offset:32768
	s_add_u32 m0, s79, s81
	s_nop 0
	global_load_lds_dwordx4 v235, s[40:41]
	ds_read_b64_tr_b16 v[58:59], v218 offset:34048
	v_mul_f32_e32 v8, v8, v166
	v_mul_f32_e32 v9, v9, v166
	v_mul_f32_e32 v10, v10, v166
	v_mul_f32_e32 v11, v11, v166
	s_add_u32 m0, m0, 0x2000
	s_nop 0
	global_load_lds_dwordx4 v236, s[40:41]
	v_mul_f32_e32 v12, v12, v166
	v_mul_f32_e32 v13, v13, v166
	v_mul_f32_e32 v14, v14, v166
	v_mul_f32_e32 v15, v15, v166
	v_mul_f32_e32 v16, v16, v166
	v_mul_f32_e32 v17, v17, v166
	global_load_dwordx2 v[148:149], v171, s[40:41]
	v_mul_f32_e32 v18, v18, v166
	v_mul_f32_e32 v19, v19, v166
	v_mul_f32_e32 v20, v20, v166
	v_mul_f32_e32 v21, v21, v166
	v_mul_f32_e32 v22, v22, v166
	global_load_dwordx2 v[150:151], v174, s[42:43] nt
	v_mul_f32_e32 v23, v23, v166
	s_waitcnt lgkmcnt(12)
	v_mfma_f32_16x16x32_bf16 v[8:11], v[96:99], v[112:115], v[8:11]
	s_waitcnt lgkmcnt(10)
	v_mfma_f32_16x16x32_bf16 v[12:15], v[96:99], v[124:127], v[12:15]
	v_mfma_f32_16x16x32_bf16 v[16:19], v[104:107], v[112:115], v[16:19]
	v_mfma_f32_16x16x32_bf16 v[20:23], v[104:107], v[124:127], v[20:23]
	s_waitcnt lgkmcnt(8)
	v_mfma_f32_16x16x32_bf16 v[8:11], v[100:103], v[120:123], v[8:11]
	global_load_dword v118, v192, s[44:45]
	s_waitcnt lgkmcnt(6)
	v_mfma_f32_16x16x32_bf16 v[12:15], v[100:103], v[128:131], v[12:15]
	v_mfma_f32_16x16x32_bf16 v[16:19], v[108:111], v[120:123], v[16:19]
	v_mfma_f32_16x16x32_bf16 v[20:23], v[108:111], v[128:131], v[20:23]
	ds_read_b128 v[96:99], v216 offset:256
	ds_read_b64 v[124:125], v220 offset:43008
	global_load_dword v152, v192, s[46:47]
	ds_read_b64 v[126:127], v220 offset:47616
	s_waitcnt lgkmcnt(8)
	v_mfma_f32_16x16x32_bf16 v[48:51], v[64:67], v[28:31], 0
	s_waitcnt lgkmcnt(7)
	v_mfma_f32_16x16x32_bf16 v[48:51], v[68:71], v[32:35], v[48:51]
	s_waitcnt lgkmcnt(6)
	v_mfma_f32_16x16x32_bf16 v[48:51], v[72:75], v[40:43], v[48:51]
	s_waitcnt lgkmcnt(5)
	v_mfma_f32_16x16x32_bf16 v[48:51], v[76:79], v[44:47], v[48:51]
	v_exp_f32_e32 v168, v167
	global_load_dword v153, v193, s[46:47]
	v_mul_f32_e32 v24, v24, v168
	v_mul_f32_e32 v25, v25, v168
	v_mul_f32_e32 v26, v26, v168
	v_mul_f32_e32 v27, v27, v168
	v_cvt_pk_bf16_f32 v156, v8, v9
	s_add_u32 s66, s54, 3
	s_cmp_lt_u32 s66, s39
	s_cselect_b32 s74, 0xc0000, 0
	s_cselect_b32 s75, 0x280000, 0
	s_cselect_b32 s76, 0x4000, 0
	s_add_u32 s40, s40, s74
	s_addc_u32 s41, s41, 0
	s_add_u32 s42, s42, s75
	s_addc_u32 s43, s43, 0
	s_add_u32 s44, s44, s76
	s_addc_u32 s45, s45, 0
	s_add_u32 s46, s46, s76
	s_addc_u32 s47, s47, 0
	v_cvt_pk_bf16_f32 v157, v10, v11
	v_cvt_pk_bf16_f32 v158, v12, v13
	s_waitcnt vmcnt(10)
	v_cvt_pk_bf16_f32 v159, v14, v15
	v_cvt_pk_bf16_f32 v160, v16, v17
	ds_write_b128 v196, v[132:135]
	v_cvt_pk_bf16_f32 v161, v18, v19
	v_cvt_pk_bf16_f32 v162, v20, v21
	ds_write_b128 v196, v[136:139] offset:8192
	v_cvt_pk_bf16_f32 v163, v22, v23
	ds_write_b64 v227, v[156:157]
	v_sub_f32_e32 v188, v117, v116
	ds_write_b64 v227, v[158:159] offset:4096
	ds_write_b64 v228, v[160:161]
	v_mul_f32_e32 v188, 0x3fb8aa3b, v188
	ds_write_b64 v228, v[162:163] offset:4096
	v_exp_f32_e32 v188, v188
	s_waitcnt lgkmcnt(6)
	v_lshlrev_b32_e32 v112, 16, v126
	v_and_b32_e32 v113, 0xffff0000, v126
	v_lshlrev_b32_e32 v184, 16, v4
	v_lshlrev_b32_e32 v114, 16, v127
	v_and_b32_e32 v115, 0xffff0000, v127
	v_and_b32_e32 v185, 0xffff0000, v4
	v_mul_f32_e32 v120, 0xbfb8aa3b, v112
	v_mul_f32_e32 v121, 0xbfb8aa3b, v113
	v_lshlrev_b32_e32 v186, 16, v5
	v_mul_f32_e32 v122, 0xbfb8aa3b, v114
	v_mul_f32_e32 v123, 0xbfb8aa3b, v115
	v_and_b32_e32 v187, 0xffff0000, v5
	v_exp_f32_e32 v120, v120
	v_exp_f32_e32 v121, v121
	v_mul_f32_e32 v184, v184, v6
	v_exp_f32_e32 v122, v122
	v_mul_f32_e32 v185, v185, v6
	v_exp_f32_e32 v123, v123
	v_add_f32_e32 v120, 1.0, v120
	v_mul_f32_e32 v186, v186, v6
	v_add_f32_e32 v121, 1.0, v121
	v_add_f32_e32 v122, 1.0, v122
	v_mul_f32_e32 v187, v187, v6
	v_add_f32_e32 v123, 1.0, v123
	v_rcp_f32_e32 v120, v120
	v_cvt_pk_bf16_f32 v190, v184, v185
	v_rcp_f32_e32 v121, v121
	v_rcp_f32_e32 v122, v122
	v_cvt_pk_bf16_f32 v191, v186, v187
	v_rcp_f32_e32 v123, v123
	v_mul_f32_e32 v112, v120, v112
	ds_write_b64 v198, v[190:191] offset:32768
	v_mul_f32_e32 v113, v121, v113
	v_mul_f32_e32 v114, v122, v114
	v_mul_f32_e32 v184, v184, v188
	v_mul_f32_e32 v115, v123, v115
	v_mul_f32_e32 v185, v185, v188
	v_lshlrev_b32_e32 v120, 16, v124
	v_and_b32_e32 v121, 0xffff0000, v124
	v_mul_f32_e32 v186, v186, v188
	v_lshlrev_b32_e32 v122, 16, v125
	v_and_b32_e32 v123, 0xffff0000, v125
	v_mul_f32_e32 v187, v187, v188
	v_sub_f32_e32 v156, v167, v96
	v_sub_f32_e32 v157, v167, v97
	v_cvt_pk_bf16_f32 v164, v184, v185
	v_sub_f32_e32 v158, v167, v98
	v_sub_f32_e32 v159, v167, v99
	v_cvt_pk_bf16_f32 v165, v186, v187
	v_exp_f32_e32 v156, v156
	v_exp_f32_e32 v157, v157
	ds_write_b64 v198, v[164:165] offset:37888
	v_exp_f32_e32 v158, v158
	ds_write_b64 v200, v[4:5] offset:43008
	v_exp_f32_e32 v159, v159
	v_mul_f32_e32 v156, v48, v156
	ds_write_b64 v200, v[36:37] offset:47616
	v_mul_f32_e32 v157, v49, v157
	v_mul_f32_e32 v158, v50, v158
	v_mul_f32_e32 v189, 0x3fb8aa3b, v116
	v_mul_f32_e32 v159, v51, v159
	v_cndmask_b32_e64 v156, 0, v156, s[14:15]
	ds_write_b32 v202, v189
	v_cndmask_b32_e64 v157, 0, v157, s[16:17]
	v_cndmask_b32_e64 v158, 0, v158, s[22:23]
	v_mul_f32_e32 v166, 0x3fb8aa3b, v117
	v_cndmask_b32_e64 v159, 0, v159, s[34:35]
	v_cvt_pk_bf16_f32 v128, v156, v157
	v_exp_f32_e32 v166, v166
	v_cvt_pk_bf16_f32 v129, v158, v159
	v_mov_b32_e32 v130, 0
	v_mov_b32_e32 v131, 0
	s_nop 1
	v_mfma_f32_16x16x32_bf16 v[24:27], v[56:59], v[128:131], v[24:27]
	s_mul_i32 s65, s56, 0x2000
	s_add_u32 s65, s65, 0x304f1000
	s_add_u32 s48, s0, s65
	s_addc_u32 s49, s1, 0
	s_nop 3
	v_fma_f32 v156, s61, v120, v24
	v_fma_f32 v157, s61, v121, v25
	v_fma_f32 v158, s61, v122, v26
	v_fma_f32 v159, s61, v123, v27
	v_mul_f32_e32 v156, v156, v112
	v_mul_f32_e32 v157, v157, v113
	v_mul_f32_e32 v158, v158, v114
	v_mul_f32_e32 v159, v159, v115
	v_cvt_pk_bf16_f32 v154, v156, v157
	v_cvt_pk_bf16_f32 v155, v158, v159
	global_store_dwordx2 v194, v[154:155], s[48:49]
	s_add_u32 s65, s54, 1
	s_sub_u32 s65, s65, s60
	s_lshl_b32 s65, s65, 6
	s_add_u32 s56, s65, s20
	s_waitcnt lgkmcnt(0)
	s_barrier
	s_mov_b32 s80, s77
	s_mov_b32 s77, s78
	s_mov_b32 s78, s79
	s_mov_b32 s79, s80
	s_add_u32 s54, s54, 1
	s_cmp_lt_u32 s54, s39
	s_cbranch_scc1 .Lssd_loop0
	s_branch .Lssd_done
; __device__ __forceinline__ void phase_ssd(const Params& P, int seg, unsigned char* smem) {
;     ...
;             bf16x8 cf[4];
; #pragma unroll
;             for (int k = 0; k < 4; ++k) cf[k] = *(const bf16x8*)(sb + T_CS + (lt * 16 + fr) * 272 + (k * 32 + fq * 8) * 2);
;             f32x4 yo = {0.f, 0.f, 0.f, 0.f};
; #pragma unroll
;             for (int k = 0; k < 4; ++k) { const bf16x8 bb = *(const bf16x8*)((const unsigned char*)StR + (pt * 16 + fr) * 272 + (k * 32 + fq * 8) * 2); yo = mfma16(cf[k], bb, yo); }
; { const f32x4 a4 = *(const f32x4*)(acP + lt * 16 + fq * 4);
; #pragma unroll
;               for (int j = 0; j < 4; ++j) yo[j] *= __expf(a4[j]); }
;             const float acl_fr = acP[lt * 16 + fr]; const int lrow = lt * 16 + fr;
; #pragma unroll
;             for (int t = 0; t < 2; ++t) {
;                 if (2 * t <= lt) {
;                     v2u xb0, xb1;
;                     { const unsigned a0 = lds0 + par * T_BUF + T_XD + (32 * t + 4 * fq + tq) * 80 + (pt * 16 + 4 * tp) * 2, a1 = a0 + 16 * 80; TR_ISSUE(xb0, a0); TR_ISSUE(xb1, a1); }
;                     float m[8];
;                     { f32x4 s0 = {0.f, 0.f, 0.f, 0.f}, s1 = {0.f, 0.f, 0.f, 0.f};
; #pragma unroll
;                       for (int k = 0; k < 4; ++k) { const bf16x8 bf0 = *(const bf16x8*)(sb + T_BS + ((2 * t) * 16 + fr) * 272 + (k * 32 + fq * 8) * 2), bf1 = *(const bf16x8*)(sb + T_BS + ((2 * t + 1) * 16 + fr) * 272 + (k * 32 + fq * 8) * 2);
;                           s0 = mfma16(bf0, cf[k], s0); s1 = mfma16(bf1, cf[k], s1); }
;                       const f32x4 a0 = *(const f32x4*)(acP + (2 * t) * 16 + fq * 4), a1 = *(const f32x4*)(acP + (2 * t + 1) * 16 + fq * 4);
; #pragma unroll
;                       for (int j = 0; j < 4; ++j) { const int si0 = (2 * t) * 16 + fq * 4 + j, si1 = si0 + 16;
;                           const float e0 = s0[j] * __expf(fminf(acl_fr - a0[j], 0.f)), e1 = s1[j] * __expf(fminf(acl_fr - a1[j], 0.f));
;                           m[j] = (si0 <= lrow) ? e0 : 0.f; m[4 + j] = (si1 <= lrow) ? e1 : 0.f; } }
;                     v4u mp; mp.x = cvt_pk_bf16(m[0], m[1]); mp.y = cvt_pk_bf16(m[2], m[3]); mp.z = cvt_pk_bf16(m[4], m[5]); mp.w = cvt_pk_bf16(m[6], m[7]);
;                     asm volatile("s_waitcnt lgkmcnt(0)" : "+v"(xb0), "+v"(xb1) :: "memory");
;                     yo = mfma16(__builtin_bit_cast(bf16x8, mp), mk8(xb0, xb1), yo);
.Lssd_loop1:
	v_add_u32_e32 v229, s77, v203
	v_add_u32_e32 v230, s77, v204
	v_add_u32_e32 v231, s77, v205
	v_add_u32_e32 v232, s77, v206
	v_add_u32_e32 v233, s77, v223
	v_add_u32_e32 v234, s77, v224
	ds_read_b128 v[28:31], v203 offset:4096
	ds_read_b128 v[32:35], v204 offset:4096
	ds_read_b128 v[40:43], v205 offset:4096
	ds_read_b128 v[44:47], v206 offset:4096
	ds_read_b128 v[48:51], v211
	ds_read_b128 v[52:55], v212
	ds_read_b128 v[56:59], v213
	ds_read_b128 v[60:63], v214
	ds_read_b32 v167, v215 offset:64
	ds_read_b64_tr_b16 v[96:97], v233
	ds_read_b64_tr_b16 v[98:99], v233 offset:4096
	ds_read_b64_tr_b16 v[100:101], v233 offset:8192
	ds_read_b64_tr_b16 v[102:103], v233 offset:12288
	ds_read_b64_tr_b16 v[104:105], v234
	ds_read_b64_tr_b16 v[106:107], v234 offset:4096
	s_waitcnt lgkmcnt(11)
	ds_read_b64_tr_b16 v[108:109], v234 offset:8192
	ds_read_b64_tr_b16 v[110:111], v234 offset:12288
	ds_read_b64_tr_b16 v[112:113], v221 offset:37888
	ds_read_b64_tr_b16 v[114:115], v221 offset:39168
	s_waitcnt lgkmcnt(11)
	ds_read_b64_tr_b16 v[124:125], v221 offset:37920
	ds_read_b64_tr_b16 v[126:127], v221 offset:39200
	ds_read_b64_tr_b16 v[120:121], v221 offset:40448
	ds_read_b64_tr_b16 v[122:123], v221 offset:41728
	s_waitcnt lgkmcnt(11)
	ds_read_b64_tr_b16 v[128:129], v221 offset:40480
	ds_read_b64_tr_b16 v[130:131], v221 offset:41760
	ds_read_b128 v[64:67], v229
	ds_read_b128 v[68:71], v230
	global_load_dwordx4 v[132:135], v169, s[40:41] offset:2048
	s_waitcnt lgkmcnt(11)
	ds_read_b128 v[72:75], v231
	ds_read_b128 v[76:79], v232
	ds_read_b128 v[80:83], v229 offset:4096
	ds_read_b128 v[84:87], v230 offset:4096
	s_waitcnt lgkmcnt(11)
	ds_read_b128 v[88:91], v231 offset:4096
	ds_read_b128 v[92:95], v232 offset:4096
	global_load_dwordx4 v[136:139], v170, s[40:41] offset:2048
	v_mfma_f32_16x16x32_bf16 v[24:27], v[48:51], v[28:31], 0
	v_mfma_f32_16x16x32_bf16 v[24:27], v[52:55], v[32:35], v[24:27]
	v_mfma_f32_16x16x32_bf16 v[24:27], v[56:59], v[40:43], v[24:27]
	v_mfma_f32_16x16x32_bf16 v[24:27], v[60:63], v[44:47], v[24:27]
	ds_read_b64_tr_b16 v[56:57], v217 offset:32768
	ds_read_b64_tr_b16 v[58:59], v217 offset:34048
	s_add_u32 m0, s79, s81
	s_nop 0
	global_load_lds_dwordx4 v235, s[40:41]
	v_mul_f32_e32 v8, v8, v166
	v_mul_f32_e32 v9, v9, v166
	v_mul_f32_e32 v10, v10, v166
	v_mul_f32_e32 v11, v11, v166
	v_mul_f32_e32 v12, v12, v166
	v_mul_f32_e32 v13, v13, v166
	v_mul_f32_e32 v14, v14, v166
	s_add_u32 m0, m0, 0x2000
	s_nop 0
	global_load_lds_dwordx4 v236, s[40:41]
	v_mul_f32_e32 v15, v15, v166
	v_mul_f32_e32 v16, v16, v166
	v_mul_f32_e32 v17, v17, v166
	v_mul_f32_e32 v18, v18, v166
	v_mul_f32_e32 v19, v19, v166
	v_mul_f32_e32 v20, v20, v166
	global_load_dwordx2 v[4:5], v171, s[40:41]
	v_mul_f32_e32 v21, v21, v166
	v_mul_f32_e32 v22, v22, v166
	v_mul_f32_e32 v23, v23, v166
	v_mfma_f32_16x16x32_bf16 v[8:11], v[96:99], v[112:115], v[8:11]
	s_waitcnt lgkmcnt(14)
	v_mfma_f32_16x16x32_bf16 v[12:15], v[96:99], v[124:127], v[12:15]
	v_mfma_f32_16x16x32_bf16 v[16:19], v[104:107], v[112:115], v[16:19]
	v_mfma_f32_16x16x32_bf16 v[20:23], v[104:107], v[124:127], v[20:23]
	global_load_dwordx2 v[36:37], v174, s[42:43] nt
	s_waitcnt lgkmcnt(12)
	v_mfma_f32_16x16x32_bf16 v[8:11], v[100:103], v[120:123], v[8:11]
	s_waitcnt lgkmcnt(10)
	v_mfma_f32_16x16x32_bf16 v[12:15], v[100:103], v[128:131], v[12:15]
	v_mfma_f32_16x16x32_bf16 v[16:19], v[108:111], v[120:123], v[16:19]
	v_mfma_f32_16x16x32_bf16 v[20:23], v[108:111], v[128:131], v[20:23]
	ds_read_b128 v[96:99], v216
	ds_read_b128 v[100:103], v216 offset:64
	global_load_dword v6, v192, s[44:45]
	ds_read_b64 v[124:125], v219 offset:44160
	ds_read_b64 v[126:127], v219 offset:48768
	s_waitcnt lgkmcnt(13)
	v_mfma_f32_16x16x32_bf16 v[48:51], v[64:67], v[28:31], 0
	s_waitcnt lgkmcnt(9)
	v_mfma_f32_16x16x32_bf16 v[52:55], v[80:83], v[28:31], 0
	v_mfma_f32_16x16x32_bf16 v[48:51], v[68:71], v[32:35], v[48:51]
	s_waitcnt lgkmcnt(8)
	v_mfma_f32_16x16x32_bf16 v[52:55], v[84:87], v[32:35], v[52:55]
	global_load_dword v116, v192, s[46:47]
	v_mfma_f32_16x16x32_bf16 v[48:51], v[72:75], v[40:43], v[48:51]
	s_waitcnt lgkmcnt(7)
	v_mfma_f32_16x16x32_bf16 v[52:55], v[88:91], v[40:43], v[52:55]
	v_mfma_f32_16x16x32_bf16 v[48:51], v[76:79], v[44:47], v[48:51]
	s_waitcnt lgkmcnt(6)
	v_mfma_f32_16x16x32_bf16 v[52:55], v[92:95], v[44:47], v[52:55]
	v_exp_f32_e32 v168, v167
	s_nop 0
	v_mul_f32_e32 v24, v24, v168
	v_mul_f32_e32 v25, v25, v168
	global_load_dword v117, v193, s[46:47]
	v_mul_f32_e32 v26, v26, v168
	v_mul_f32_e32 v27, v27, v168
	v_cvt_pk_bf16_f32 v156, v8, v9
	v_cvt_pk_bf16_f32 v157, v10, v11
	v_cvt_pk_bf16_f32 v158, v12, v13
	v_cvt_pk_bf16_f32 v159, v14, v15
	s_add_u32 s66, s54, 3
	s_cmp_lt_u32 s66, s39
	s_cselect_b32 s74, 0xc0000, 0
	s_cselect_b32 s75, 0x280000, 0
	s_cselect_b32 s76, 0x4000, 0
	s_add_u32 s40, s40, s74
	s_addc_u32 s41, s41, 0
	s_add_u32 s42, s42, s75
	s_addc_u32 s43, s43, 0
	s_add_u32 s44, s44, s76
	s_addc_u32 s45, s45, 0
	s_add_u32 s46, s46, s76
	s_addc_u32 s47, s47, 0
	v_cvt_pk_bf16_f32 v160, v16, v17
	v_cvt_pk_bf16_f32 v161, v18, v19
	s_waitcnt vmcnt(10)
	v_cvt_pk_bf16_f32 v162, v20, v21
	v_cvt_pk_bf16_f32 v163, v22, v23
	ds_write_b64 v227, v[156:157] offset:8192
	ds_write_b128 v197, v[140:143]
	ds_write_b64 v227, v[158:159] offset:12288
	ds_write_b64 v228, v[160:161] offset:8192
	ds_write_b128 v197, v[144:147] offset:8192
	ds_write_b64 v228, v[162:163] offset:12288
	s_waitcnt lgkmcnt(6)
; __device__ __forceinline__ void phase_ssd(const Params& P, int seg, unsigned char* smem) {
;     ...
;                       for (int k = 0; k < 4; ++k) { const bf16x8 bf0 = *(const bf16x8*)(sb + T_BS + ((2 * t) * 16 + fr) * 272 + (k * 32 + fq * 8) * 2), bf1 = *(const bf16x8*)(sb + T_BS + ((2 * t + 1) * 16 + fr) * 272 + (k * 32 + fq * 8) * 2);
;                           s0 = mfma16(bf0, cf[k], s0); s1 = mfma16(bf1, cf[k], s1); }
;                       const f32x4 a0 = *(const f32x4*)(acP + (2 * t) * 16 + fq * 4), a1 = *(const f32x4*)(acP + (2 * t + 1) * 16 + fq * 4);
; #pragma unroll
;                       for (int j = 0; j < 4; ++j) { const int si0 = (2 * t) * 16 + fq * 4 + j, si1 = si0 + 16;
;                           const float e0 = s0[j] * __expf(fminf(acl_fr - a0[j], 0.f)), e1 = s1[j] * __expf(fminf(acl_fr - a1[j], 0.f));
;                           m[j] = (si0 <= lrow) ? e0 : 0.f; m[4 + j] = (si1 <= lrow) ? e1 : 0.f; } }
;                     v4u mp; mp.x = cvt_pk_bf16(m[0], m[1]); mp.y = cvt_pk_bf16(m[2], m[3]); mp.z = cvt_pk_bf16(m[4], m[5]); mp.w = cvt_pk_bf16(m[6], m[7]);
;                     asm volatile("s_waitcnt lgkmcnt(0)" : "+v"(xb0), "+v"(xb1) :: "memory");
;                     yo = mfma16(__builtin_bit_cast(bf16x8, mp), mk8(xb0, xb1), yo);
;                 }
;             }
; #pragma unroll
;             for (int j = 0; j < 4; ++j) { const int l = lt * 16 + fq * 4 + j, p = pt * 16 + fr; const float xv = bf2f(*(const bf16*)(sb + T_XS + l * 64 + p * 2)), zv = bf2f(*(const bf16*)(sb + T_ZS + l * 64 + p * 2));
;                 ypre[(size_t)(row0 + l) * DINNER + h * 64 + ph * 32 + p] = f2bfh((yo[j] + Dh * xv) * siluf_(zv)); }
;             { v2u xa[2][2][2], bb[2][2];
; #pragma unroll
;               for (int kk = 0; kk < 2; ++kk) {
; #pragma unroll
;                   for (int hh = 0; hh < 2; ++hh) { const int r = kk * 32 + 8 * fq + 4 * hh + tq;
;                       TR_ISSUE(bb[kk][hh], lds0 + par * T_BUF + T_BS + r * 272 + (w * 16 + 4 * tp) * 2);
; #pragma unroll
;                       for (int p2 = 0; p2 < 2; ++p2) TR_ISSUE(xa[p2][kk][hh], lds0 + par * T_BUF + T_XE + r * 80 + (p2 * 16 + 4 * tp) * 2); } }
;               asm volatile("s_waitcnt lgkmcnt(0)" : "+v"(xa[0][0][0]), "+v"(xa[0][0][1]), "+v"(xa[0][1][0]), "+v"(xa[0][1][1]), "+v"(xa[1][0][0]), "+v"(xa[1][0][1]), "+v"(xa[1][1][0]), "+v"(xa[1][1][1]),
	v_lshlrev_b32_e32 v112, 16, v126
	v_sub_f32_e32 v188, v153, v152
	v_and_b32_e32 v113, 0xffff0000, v126
	v_lshlrev_b32_e32 v114, 16, v127
	v_mul_f32_e32 v188, 0x3fb8aa3b, v188
	v_and_b32_e32 v115, 0xffff0000, v127
	v_mul_f32_e32 v120, 0xbfb8aa3b, v112
	v_exp_f32_e32 v188, v188
	v_mul_f32_e32 v121, 0xbfb8aa3b, v113
	v_mul_f32_e32 v122, 0xbfb8aa3b, v114
	v_lshlrev_b32_e32 v184, 16, v148
	v_mul_f32_e32 v123, 0xbfb8aa3b, v115
	v_exp_f32_e32 v120, v120
	v_and_b32_e32 v185, 0xffff0000, v148
	v_exp_f32_e32 v121, v121
	v_exp_f32_e32 v122, v122
	v_lshlrev_b32_e32 v186, 16, v149
	v_exp_f32_e32 v123, v123
	v_add_f32_e32 v120, 1.0, v120
	v_add_f32_e32 v121, 1.0, v121
	v_and_b32_e32 v187, 0xffff0000, v149
	v_add_f32_e32 v122, 1.0, v122
	v_add_f32_e32 v123, 1.0, v123
	v_mul_f32_e32 v184, v184, v118
	v_rcp_f32_e32 v120, v120
	v_rcp_f32_e32 v121, v121
	v_mul_f32_e32 v185, v185, v118
	v_rcp_f32_e32 v122, v122
	v_rcp_f32_e32 v123, v123
	v_mul_f32_e32 v186, v186, v118
	v_mul_f32_e32 v112, v120, v112
	v_mul_f32_e32 v113, v121, v113
	v_mul_f32_e32 v187, v187, v118
	v_mul_f32_e32 v114, v122, v114
	v_mul_f32_e32 v115, v123, v115
	v_cvt_pk_bf16_f32 v190, v184, v185
	v_lshlrev_b32_e32 v120, 16, v124
	v_and_b32_e32 v121, 0xffff0000, v124
	v_cvt_pk_bf16_f32 v191, v186, v187
	v_lshlrev_b32_e32 v122, 16, v125
	v_and_b32_e32 v123, 0xffff0000, v125
	v_sub_f32_e32 v156, v167, v96
	ds_write_b64 v199, v[190:191] offset:32768
	v_sub_f32_e32 v157, v167, v97
	v_sub_f32_e32 v158, v167, v98
	v_mul_f32_e32 v184, v184, v188
	v_sub_f32_e32 v159, v167, v99
	v_exp_f32_e32 v156, v156
	v_mul_f32_e32 v185, v185, v188
	v_exp_f32_e32 v157, v157
	v_exp_f32_e32 v158, v158
	v_mul_f32_e32 v186, v186, v188
	v_exp_f32_e32 v159, v159
	v_mul_f32_e32 v156, v48, v156
	v_mul_f32_e32 v187, v187, v188
	v_mul_f32_e32 v157, v49, v157
	v_mul_f32_e32 v158, v50, v158
	v_cvt_pk_bf16_f32 v164, v184, v185
	v_mul_f32_e32 v159, v51, v159
	v_sub_f32_e32 v160, v167, v100
	v_cvt_pk_bf16_f32 v165, v186, v187
	v_sub_f32_e32 v161, v167, v101
	v_sub_f32_e32 v162, v167, v102
	v_sub_f32_e32 v163, v167, v103
	ds_write_b64 v199, v[164:165] offset:37888
	v_exp_f32_e32 v160, v160
	v_exp_f32_e32 v161, v161
	ds_write_b64 v201, v[148:149] offset:43008
	v_exp_f32_e32 v162, v162
	v_exp_f32_e32 v163, v163
	ds_write_b64 v201, v[150:151] offset:47616
	v_mul_f32_e32 v160, v52, v160
	v_mul_f32_e32 v161, v53, v161
	v_mul_f32_e32 v189, 0x3fb8aa3b, v152
	v_mul_f32_e32 v162, v54, v162
	v_mul_f32_e32 v163, v55, v163
	ds_write_b32 v202, v189 offset:256
	v_cndmask_b32_e64 v160, 0, v160, s[14:15]
	v_cndmask_b32_e64 v161, 0, v161, s[16:17]
	v_mul_f32_e32 v166, 0x3fb8aa3b, v153
	v_cndmask_b32_e64 v162, 0, v162, s[22:23]
	v_cndmask_b32_e64 v163, 0, v163, s[34:35]
	v_exp_f32_e32 v166, v166
	v_cvt_pk_bf16_f32 v128, v156, v157
	v_cvt_pk_bf16_f32 v129, v158, v159
	v_cvt_pk_bf16_f32 v130, v160, v161
	v_cvt_pk_bf16_f32 v131, v162, v163
	s_nop 1
	v_mfma_f32_16x16x32_bf16 v[24:27], v[56:59], v[128:131], v[24:27]
	s_mul_i32 s65, s56, 0x2000
	s_add_u32 s65, s65, 0x304f1000
	s_add_u32 s48, s0, s65
	s_addc_u32 s49, s1, 0
	s_nop 3
	v_fma_f32 v156, s61, v120, v24
	v_fma_f32 v157, s61, v121, v25
	v_fma_f32 v158, s61, v122, v26
	v_fma_f32 v159, s61, v123, v27
	v_mul_f32_e32 v156, v156, v112
	v_mul_f32_e32 v157, v157, v113
	v_mul_f32_e32 v158, v158, v114
	v_mul_f32_e32 v159, v159, v115
	v_cvt_pk_bf16_f32 v154, v156, v157
	v_cvt_pk_bf16_f32 v155, v158, v159
	global_store_dwordx2 v194, v[154:155], s[48:49]
	s_add_u32 s65, s54, 1
	s_sub_u32 s65, s65, s60
	s_lshl_b32 s65, s65, 6
	s_add_u32 s56, s65, s20
	s_waitcnt lgkmcnt(0)
	s_barrier
	s_mov_b32 s80, s77
	s_mov_b32 s77, s78
	s_mov_b32 s78, s79
	s_mov_b32 s79, s80
	s_add_u32 s54, s54, 1
	s_cmp_ge_u32 s54, s39
	s_cbranch_scc1 .Lssd_done
	v_add_u32_e32 v229, s77, v203
	v_add_u32_e32 v230, s77, v204
	v_add_u32_e32 v231, s77, v205
	v_add_u32_e32 v232, s77, v206
	v_add_u32_e32 v233, s77, v223
	v_add_u32_e32 v234, s77, v224
	ds_read_b128 v[28:31], v207 offset:4096
	ds_read_b128 v[32:35], v208 offset:4096
	ds_read_b128 v[40:43], v209 offset:4096
	ds_read_b128 v[44:47], v210 offset:4096
	ds_read_b128 v[48:51], v211 offset:8192
	ds_read_b128 v[52:55], v212 offset:8192
	ds_read_b128 v[56:59], v213 offset:8192
	ds_read_b128 v[60:63], v214 offset:8192
	ds_read_b32 v167, v215 offset:320
	ds_read_b64_tr_b16 v[96:97], v233
	ds_read_b64_tr_b16 v[98:99], v233 offset:4096
	ds_read_b64_tr_b16 v[100:101], v233 offset:8192
	ds_read_b64_tr_b16 v[102:103], v233 offset:12288
	ds_read_b64_tr_b16 v[104:105], v234
	ds_read_b64_tr_b16 v[106:107], v234 offset:4096
	s_waitcnt lgkmcnt(11)
	ds_read_b64_tr_b16 v[108:109], v234 offset:8192
	ds_read_b64_tr_b16 v[110:111], v234 offset:12288
	ds_read_b64_tr_b16 v[112:113], v222 offset:37888
	ds_read_b64_tr_b16 v[114:115], v222 offset:39168
	s_waitcnt lgkmcnt(11)
	ds_read_b64_tr_b16 v[124:125], v222 offset:37920
	ds_read_b64_tr_b16 v[126:127], v222 offset:39200
	ds_read_b64_tr_b16 v[120:121], v222 offset:40448
	ds_read_b64_tr_b16 v[122:123], v222 offset:41728
	s_waitcnt lgkmcnt(11)
	ds_read_b64_tr_b16 v[128:129], v222 offset:40480
	ds_read_b64_tr_b16 v[130:131], v222 offset:41760
	ds_read_b128 v[64:67], v229
	ds_read_b128 v[68:71], v230
	global_load_dwordx4 v[140:143], v169, s[40:41] offset:2048
	s_waitcnt lgkmcnt(11)
	ds_read_b128 v[72:75], v231
	ds_read_b128 v[76:79], v232
	ds_read_b128 v[80:83], v229 offset:4096
	ds_read_b128 v[84:87], v230 offset:4096
	s_waitcnt lgkmcnt(11)
; __device__ __forceinline__ void phase_ssd(const Params& P, int seg, unsigned char* smem) {
;     ...
;             for (int k = 0; k < 4; ++k) cf[k] = *(const bf16x8*)(sb + T_CS + (lt * 16 + fr) * 272 + (k * 32 + fq * 8) * 2);
;             f32x4 yo = {0.f, 0.f, 0.f, 0.f};
; #pragma unroll
;             for (int k = 0; k < 4; ++k) { const bf16x8 bb = *(const bf16x8*)((const unsigned char*)StR + (pt * 16 + fr) * 272 + (k * 32 + fq * 8) * 2); yo = mfma16(cf[k], bb, yo); }
; { const f32x4 a4 = *(const f32x4*)(acP + lt * 16 + fq * 4);
; #pragma unroll
;               for (int j = 0; j < 4; ++j) yo[j] *= __expf(a4[j]); }
;             const float acl_fr = acP[lt * 16 + fr]; const int lrow = lt * 16 + fr;
; #pragma unroll
;             for (int t = 0; t < 2; ++t) {
;                 if (2 * t <= lt) {
;                     v2u xb0, xb1;
;                     { const unsigned a0 = lds0 + par * T_BUF + T_XD + (32 * t + 4 * fq + tq) * 80 + (pt * 16 + 4 * tp) * 2, a1 = a0 + 16 * 80; TR_ISSUE(xb0, a0); TR_ISSUE(xb1, a1); }
;                     float m[8];
;                     { f32x4 s0 = {0.f, 0.f, 0.f, 0.f}, s1 = {0.f, 0.f, 0.f, 0.f};
; #pragma unroll
;                       for (int k = 0; k < 4; ++k) { const bf16x8 bf0 = *(const bf16x8*)(sb + T_BS + ((2 * t) * 16 + fr) * 272 + (k * 32 + fq * 8) * 2), bf1 = *(const bf16x8*)(sb + T_BS + ((2 * t + 1) * 16 + fr) * 272 + (k * 32 + fq * 8) * 2);
;                           s0 = mfma16(bf0, cf[k], s0); s1 = mfma16(bf1, cf[k], s1); }
;                       const f32x4 a0 = *(const f32x4*)(acP + (2 * t) * 16 + fq * 4), a1 = *(const f32x4*)(acP + (2 * t + 1) * 16 + fq * 4);
; #pragma unroll
;                       for (int j = 0; j < 4; ++j) { const int si0 = (2 * t) * 16 + fq * 4 + j, si1 = si0 + 16;
;                           const float e0 = s0[j] * __expf(fminf(acl_fr - a0[j], 0.f)), e1 = s1[j] * __expf(fminf(acl_fr - a1[j], 0.f));
;                           m[j] = (si0 <= lrow) ? e0 : 0.f; m[4 + j] = (si1 <= lrow) ? e1 : 0.f; } }
;                     v4u mp; mp.x = cvt_pk_bf16(m[0], m[1]); mp.y = cvt_pk_bf16(m[2], m[3]); mp.z = cvt_pk_bf16(m[4], m[5]); mp.w = cvt_pk_bf16(m[6], m[7]);
;                     asm volatile("s_waitcnt lgkmcnt(0)" : "+v"(xb0), "+v"(xb1) :: "memory");
;                     yo = mfma16(__builtin_bit_cast(bf16x8, mp), mk8(xb0, xb1), yo);
;                 }
;             }
; #pragma unroll
	ds_read_b128 v[88:91], v231 offset:4096
	ds_read_b128 v[92:95], v232 offset:4096
	global_load_dwordx4 v[144:147], v170, s[40:41] offset:2048
	v_mfma_f32_16x16x32_bf16 v[24:27], v[48:51], v[28:31], 0
	v_mfma_f32_16x16x32_bf16 v[24:27], v[52:55], v[32:35], v[24:27]
	v_mfma_f32_16x16x32_bf16 v[24:27], v[56:59], v[40:43], v[24:27]
	v_mfma_f32_16x16x32_bf16 v[24:27], v[60:63], v[44:47], v[24:27]
	ds_read_b64_tr_b16 v[56:57], v218 offset:32768
	ds_read_b64_tr_b16 v[58:59], v218 offset:34048
	s_add_u32 m0, s79, s81
	s_nop 0
	global_load_lds_dwordx4 v235, s[40:41]
	v_mul_f32_e32 v8, v8, v166
	v_mul_f32_e32 v9, v9, v166
	v_mul_f32_e32 v10, v10, v166
	v_mul_f32_e32 v11, v11, v166
	v_mul_f32_e32 v12, v12, v166
	v_mul_f32_e32 v13, v13, v166
	v_mul_f32_e32 v14, v14, v166
	s_add_u32 m0, m0, 0x2000
	s_nop 0
	global_load_lds_dwordx4 v236, s[40:41]
	v_mul_f32_e32 v15, v15, v166
	v_mul_f32_e32 v16, v16, v166
	v_mul_f32_e32 v17, v17, v166
	v_mul_f32_e32 v18, v18, v166
	v_mul_f32_e32 v19, v19, v166
	v_mul_f32_e32 v20, v20, v166
	global_load_dwordx2 v[148:149], v171, s[40:41]
	v_mul_f32_e32 v21, v21, v166
	v_mul_f32_e32 v22, v22, v166
	v_mul_f32_e32 v23, v23, v166
	v_mfma_f32_16x16x32_bf16 v[8:11], v[96:99], v[112:115], v[8:11]
	s_waitcnt lgkmcnt(14)
	v_mfma_f32_16x16x32_bf16 v[12:15], v[96:99], v[124:127], v[12:15]
	v_mfma_f32_16x16x32_bf16 v[16:19], v[104:107], v[112:115], v[16:19]
	v_mfma_f32_16x16x32_bf16 v[20:23], v[104:107], v[124:127], v[20:23]
	global_load_dwordx2 v[150:151], v174, s[42:43] nt
	s_waitcnt lgkmcnt(12)
	v_mfma_f32_16x16x32_bf16 v[8:11], v[100:103], v[120:123], v[8:11]
	s_waitcnt lgkmcnt(10)
	v_mfma_f32_16x16x32_bf16 v[12:15], v[100:103], v[128:131], v[12:15]
	v_mfma_f32_16x16x32_bf16 v[16:19], v[108:111], v[120:123], v[16:19]
	v_mfma_f32_16x16x32_bf16 v[20:23], v[108:111], v[128:131], v[20:23]
	ds_read_b128 v[96:99], v216 offset:256
	ds_read_b128 v[100:103], v216 offset:320
	global_load_dword v118, v192, s[44:45]
	ds_read_b64 v[124:125], v220 offset:44160
	ds_read_b64 v[126:127], v220 offset:48768
	s_waitcnt lgkmcnt(13)
	v_mfma_f32_16x16x32_bf16 v[48:51], v[64:67], v[28:31], 0
	s_waitcnt lgkmcnt(9)
	v_mfma_f32_16x16x32_bf16 v[52:55], v[80:83], v[28:31], 0
	v_mfma_f32_16x16x32_bf16 v[48:51], v[68:71], v[32:35], v[48:51]
	s_waitcnt lgkmcnt(8)
	v_mfma_f32_16x16x32_bf16 v[52:55], v[84:87], v[32:35], v[52:55]
	global_load_dword v152, v192, s[46:47]
	v_mfma_f32_16x16x32_bf16 v[48:51], v[72:75], v[40:43], v[48:51]
	s_waitcnt lgkmcnt(7)
	v_mfma_f32_16x16x32_bf16 v[52:55], v[88:91], v[40:43], v[52:55]
	v_mfma_f32_16x16x32_bf16 v[48:51], v[76:79], v[44:47], v[48:51]
	s_waitcnt lgkmcnt(6)
	v_mfma_f32_16x16x32_bf16 v[52:55], v[92:95], v[44:47], v[52:55]
	v_exp_f32_e32 v168, v167
	s_nop 0
	v_mul_f32_e32 v24, v24, v168
	v_mul_f32_e32 v25, v25, v168
	global_load_dword v153, v193, s[46:47]
	v_mul_f32_e32 v26, v26, v168
	v_mul_f32_e32 v27, v27, v168
	v_cvt_pk_bf16_f32 v156, v8, v9
	v_cvt_pk_bf16_f32 v157, v10, v11
	v_cvt_pk_bf16_f32 v158, v12, v13
	v_cvt_pk_bf16_f32 v159, v14, v15
	s_add_u32 s66, s54, 3
	s_cmp_lt_u32 s66, s39
	s_cselect_b32 s74, 0xc0000, 0
	s_cselect_b32 s75, 0x280000, 0
	s_cselect_b32 s76, 0x4000, 0
	s_add_u32 s40, s40, s74
	s_addc_u32 s41, s41, 0
	s_add_u32 s42, s42, s75
	s_addc_u32 s43, s43, 0
	s_add_u32 s44, s44, s76
	s_addc_u32 s45, s45, 0
	s_add_u32 s46, s46, s76
	s_addc_u32 s47, s47, 0
	v_cvt_pk_bf16_f32 v160, v16, v17
	v_cvt_pk_bf16_f32 v161, v18, v19
	s_waitcnt vmcnt(10)
	v_cvt_pk_bf16_f32 v162, v20, v21
	v_cvt_pk_bf16_f32 v163, v22, v23
	ds_write_b64 v227, v[156:157]
	ds_write_b128 v196, v[132:135]
	ds_write_b64 v227, v[158:159] offset:4096
	ds_write_b64 v228, v[160:161]
	ds_write_b128 v196, v[136:139] offset:8192
	ds_write_b64 v228, v[162:163] offset:4096
	s_waitcnt lgkmcnt(6)
	v_lshlrev_b32_e32 v112, 16, v126
	v_sub_f32_e32 v188, v117, v116
	v_and_b32_e32 v113, 0xffff0000, v126
	v_lshlrev_b32_e32 v114, 16, v127
	v_mul_f32_e32 v188, 0x3fb8aa3b, v188
	v_and_b32_e32 v115, 0xffff0000, v127
	v_mul_f32_e32 v120, 0xbfb8aa3b, v112
	v_exp_f32_e32 v188, v188
	v_mul_f32_e32 v121, 0xbfb8aa3b, v113
	v_mul_f32_e32 v122, 0xbfb8aa3b, v114
	v_lshlrev_b32_e32 v184, 16, v4
	v_mul_f32_e32 v123, 0xbfb8aa3b, v115
	v_exp_f32_e32 v120, v120
	v_and_b32_e32 v185, 0xffff0000, v4
	v_exp_f32_e32 v121, v121
	v_exp_f32_e32 v122, v122
	v_lshlrev_b32_e32 v186, 16, v5
	v_exp_f32_e32 v123, v123
	v_add_f32_e32 v120, 1.0, v120
	v_add_f32_e32 v121, 1.0, v121
	v_and_b32_e32 v187, 0xffff0000, v5
	v_add_f32_e32 v122, 1.0, v122
	v_add_f32_e32 v123, 1.0, v123
	v_mul_f32_e32 v184, v184, v6
	v_rcp_f32_e32 v120, v120
	v_rcp_f32_e32 v121, v121
	v_mul_f32_e32 v185, v185, v6
	v_rcp_f32_e32 v122, v122
	v_rcp_f32_e32 v123, v123
	v_mul_f32_e32 v186, v186, v6
	v_mul_f32_e32 v112, v120, v112
	v_mul_f32_e32 v113, v121, v113
	v_mul_f32_e32 v187, v187, v6
	v_mul_f32_e32 v114, v122, v114
	v_mul_f32_e32 v115, v123, v115
	v_cvt_pk_bf16_f32 v190, v184, v185
	v_lshlrev_b32_e32 v120, 16, v124
	v_and_b32_e32 v121, 0xffff0000, v124
	v_cvt_pk_bf16_f32 v191, v186, v187
	v_lshlrev_b32_e32 v122, 16, v125
	v_and_b32_e32 v123, 0xffff0000, v125
	v_sub_f32_e32 v156, v167, v96
	ds_write_b64 v198, v[190:191] offset:32768
	v_sub_f32_e32 v157, v167, v97
	v_sub_f32_e32 v158, v167, v98
	v_mul_f32_e32 v184, v184, v188
	v_sub_f32_e32 v159, v167, v99
	v_exp_f32_e32 v156, v156
	v_mul_f32_e32 v185, v185, v188
	v_exp_f32_e32 v157, v157
	v_exp_f32_e32 v158, v158
	v_mul_f32_e32 v186, v186, v188
	v_exp_f32_e32 v159, v159
	v_mul_f32_e32 v156, v48, v156
	v_mul_f32_e32 v187, v187, v188
	v_mul_f32_e32 v157, v49, v157
	v_mul_f32_e32 v158, v50, v158
	v_cvt_pk_bf16_f32 v164, v184, v185
	v_mul_f32_e32 v159, v51, v159
; __device__ __forceinline__ bf16 f2bfh(float f) { return (bf16)(cvt_pk_bf16(f, f) & 0xffffu); }
; __device__ __forceinline__ void phase_ssd(const Params& P, int seg, unsigned char* smem) {
;     ...
;             bf16x8 cf[4];
; #pragma unroll
;             for (int k = 0; k < 4; ++k) cf[k] = *(const bf16x8*)(sb + T_CS + (lt * 16 + fr) * 272 + (k * 32 + fq * 8) * 2);
;             f32x4 yo = {0.f, 0.f, 0.f, 0.f};
; #pragma unroll
;             for (int k = 0; k < 4; ++k) { const bf16x8 bb = *(const bf16x8*)((const unsigned char*)StR + (pt * 16 + fr) * 272 + (k * 32 + fq * 8) * 2); yo = mfma16(cf[k], bb, yo); }
; { const f32x4 a4 = *(const f32x4*)(acP + lt * 16 + fq * 4);
; #pragma unroll
;               for (int j = 0; j < 4; ++j) yo[j] *= __expf(a4[j]); }
;             const float acl_fr = acP[lt * 16 + fr]; const int lrow = lt * 16 + fr;
; #pragma unroll
;             for (int t = 0; t < 2; ++t) {
;                 if (2 * t <= lt) {
;                     v2u xb0, xb1;
;                     { const unsigned a0 = lds0 + par * T_BUF + T_XD + (32 * t + 4 * fq + tq) * 80 + (pt * 16 + 4 * tp) * 2, a1 = a0 + 16 * 80; TR_ISSUE(xb0, a0); TR_ISSUE(xb1, a1); }
;                     float m[8];
;                     { f32x4 s0 = {0.f, 0.f, 0.f, 0.f}, s1 = {0.f, 0.f, 0.f, 0.f};
; #pragma unroll
;     ...
;                       for (int j = 0; j < 4; ++j) { const int si0 = (2 * t) * 16 + fq * 4 + j, si1 = si0 + 16;
;                           const float e0 = s0[j] * __expf(fminf(acl_fr - a0[j], 0.f)), e1 = s1[j] * __expf(fminf(acl_fr - a1[j], 0.f));
;                           m[j] = (si0 <= lrow) ? e0 : 0.f; m[4 + j] = (si1 <= lrow) ? e1 : 0.f; } }
;                     v4u mp; mp.x = cvt_pk_bf16(m[0], m[1]); mp.y = cvt_pk_bf16(m[2], m[3]); mp.z = cvt_pk_bf16(m[4], m[5]); mp.w = cvt_pk_bf16(m[6], m[7]);
;                     asm volatile("s_waitcnt lgkmcnt(0)" : "+v"(xb0), "+v"(xb1) :: "memory");
;                     yo = mfma16(__builtin_bit_cast(bf16x8, mp), mk8(xb0, xb1), yo);
;                 }
;             }
; #pragma unroll
;             for (int j = 0; j < 4; ++j) { const int l = lt * 16 + fq * 4 + j, p = pt * 16 + fr; const float xv = bf2f(*(const bf16*)(sb + T_XS + l * 64 + p * 2)), zv = bf2f(*(const bf16*)(sb + T_ZS + l * 64 + p * 2));
;                 ypre[(size_t)(row0 + l) * DINNER + h * 64 + ph * 32 + p] = f2bfh((yo[j] + Dh * xv) * siluf_(zv)); }
	v_sub_f32_e32 v160, v167, v100
	v_cvt_pk_bf16_f32 v165, v186, v187
	v_sub_f32_e32 v161, v167, v101
	v_sub_f32_e32 v162, v167, v102
	v_sub_f32_e32 v163, v167, v103
	ds_write_b64 v198, v[164:165] offset:37888
	v_exp_f32_e32 v160, v160
	v_exp_f32_e32 v161, v161
	ds_write_b64 v200, v[4:5] offset:43008
	v_exp_f32_e32 v162, v162
	v_exp_f32_e32 v163, v163
	ds_write_b64 v200, v[36:37] offset:47616
	v_mul_f32_e32 v160, v52, v160
	v_mul_f32_e32 v161, v53, v161
	v_mul_f32_e32 v189, 0x3fb8aa3b, v116
	v_mul_f32_e32 v162, v54, v162
	v_mul_f32_e32 v163, v55, v163
	ds_write_b32 v202, v189
	v_cndmask_b32_e64 v160, 0, v160, s[14:15]
	v_cndmask_b32_e64 v161, 0, v161, s[16:17]
	v_mul_f32_e32 v166, 0x3fb8aa3b, v117
	v_cndmask_b32_e64 v162, 0, v162, s[22:23]
	v_cndmask_b32_e64 v163, 0, v163, s[34:35]
	v_exp_f32_e32 v166, v166
	v_cvt_pk_bf16_f32 v128, v156, v157
	v_cvt_pk_bf16_f32 v129, v158, v159
	v_cvt_pk_bf16_f32 v130, v160, v161
	v_cvt_pk_bf16_f32 v131, v162, v163
	s_nop 1
	v_mfma_f32_16x16x32_bf16 v[24:27], v[56:59], v[128:131], v[24:27]
	s_mul_i32 s65, s56, 0x2000
	s_add_u32 s65, s65, 0x304f1000
	s_add_u32 s48, s0, s65
	s_addc_u32 s49, s1, 0
	s_nop 3
	v_fma_f32 v156, s61, v120, v24
	v_fma_f32 v157, s61, v121, v25
	v_fma_f32 v158, s61, v122, v26
	v_fma_f32 v159, s61, v123, v27
	v_mul_f32_e32 v156, v156, v112
	v_mul_f32_e32 v157, v157, v113
	v_mul_f32_e32 v158, v158, v114
	v_mul_f32_e32 v159, v159, v115
	v_cvt_pk_bf16_f32 v154, v156, v157
	v_cvt_pk_bf16_f32 v155, v158, v159
	global_store_dwordx2 v194, v[154:155], s[48:49]
	s_add_u32 s65, s54, 1
	s_sub_u32 s65, s65, s60
	s_lshl_b32 s65, s65, 6
	s_add_u32 s56, s65, s20
	s_waitcnt lgkmcnt(0)
	s_barrier
	s_mov_b32 s80, s77
	s_mov_b32 s77, s78
	s_mov_b32 s78, s79
	s_mov_b32 s79, s80
	s_add_u32 s54, s54, 1
	s_cmp_lt_u32 s54, s39
	s_cbranch_scc1 .Lssd_loop1
	s_branch .Lssd_done
.Lssd_loop2:
	v_add_u32_e32 v229, s77, v203
	v_add_u32_e32 v230, s77, v204
	v_add_u32_e32 v231, s77, v205
	v_add_u32_e32 v232, s77, v206
	ds_read_b128 v[28:31], v203 offset:8192
	ds_read_b128 v[32:35], v204 offset:8192
	ds_read_b128 v[40:43], v205 offset:8192
	ds_read_b128 v[44:47], v206 offset:8192
	ds_read_b128 v[48:51], v211
	ds_read_b128 v[52:55], v212
	ds_read_b128 v[56:59], v213
	ds_read_b128 v[60:63], v214
	ds_read_b32 v167, v215 offset:128
	ds_read_b128 v[64:67], v229
	ds_read_b128 v[68:71], v230
	ds_read_b128 v[72:75], v231
	ds_read_b128 v[76:79], v232
	ds_read_b128 v[80:83], v229 offset:4096
	ds_read_b128 v[84:87], v230 offset:4096
	global_load_dwordx4 v[132:135], v169, s[40:41] offset:2048
	s_waitcnt lgkmcnt(11)
	ds_read_b128 v[88:91], v231 offset:4096
	ds_read_b128 v[92:95], v232 offset:4096
	ds_read_b128 v[96:99], v216
	ds_read_b128 v[100:103], v216 offset:64
	s_waitcnt lgkmcnt(11)
	ds_read_b64 v[124:125], v219 offset:45312
	global_load_dwordx4 v[136:139], v170, s[40:41] offset:2048
	ds_read_b64 v[126:127], v219 offset:49920
	v_mfma_f32_16x16x32_bf16 v[24:27], v[48:51], v[28:31], 0
	v_mfma_f32_16x16x32_bf16 v[24:27], v[52:55], v[32:35], v[24:27]
	v_mfma_f32_16x16x32_bf16 v[24:27], v[56:59], v[40:43], v[24:27]
	v_mfma_f32_16x16x32_bf16 v[24:27], v[60:63], v[44:47], v[24:27]
	ds_read_b64_tr_b16 v[56:57], v217 offset:32768
	s_add_u32 m0, s79, s81
	s_nop 0
	global_load_lds_dwordx4 v235, s[40:41]
	ds_read_b64_tr_b16 v[58:59], v217 offset:34048
	s_waitcnt lgkmcnt(13)
	v_mfma_f32_16x16x32_bf16 v[48:51], v[64:67], v[28:31], 0
	s_waitcnt lgkmcnt(9)
	v_mfma_f32_16x16x32_bf16 v[52:55], v[80:83], v[28:31], 0
	v_mfma_f32_16x16x32_bf16 v[48:51], v[68:71], v[32:35], v[48:51]
	s_waitcnt lgkmcnt(8)
	v_mfma_f32_16x16x32_bf16 v[52:55], v[84:87], v[32:35], v[52:55]
	v_mfma_f32_16x16x32_bf16 v[48:51], v[72:75], v[40:43], v[48:51]
	s_add_u32 m0, m0, 0x2000
	s_nop 0
	global_load_lds_dwordx4 v236, s[40:41]
	s_waitcnt lgkmcnt(7)
	v_mfma_f32_16x16x32_bf16 v[52:55], v[88:91], v[40:43], v[52:55]
	v_mfma_f32_16x16x32_bf16 v[48:51], v[76:79], v[44:47], v[48:51]
	s_waitcnt lgkmcnt(6)
	v_mfma_f32_16x16x32_bf16 v[52:55], v[92:95], v[44:47], v[52:55]
	ds_read_b128 v[64:67], v229 offset:8192
	ds_read_b128 v[68:71], v230 offset:8192
	ds_read_b128 v[72:75], v231 offset:8192
	global_load_dwordx2 v[4:5], v171, s[40:41]
	ds_read_b128 v[76:79], v232 offset:8192
	ds_read_b64_tr_b16 v[60:61], v217 offset:35328
	ds_read_b64_tr_b16 v[62:63], v217 offset:36608
	v_exp_f32_e32 v168, v167
	s_nop 0
	v_mul_f32_e32 v24, v24, v168
	global_load_dwordx2 v[36:37], v174, s[42:43] nt
	v_mul_f32_e32 v25, v25, v168
	v_mul_f32_e32 v26, v26, v168
	v_mul_f32_e32 v27, v27, v168
	s_waitcnt lgkmcnt(8)
	v_lshlrev_b32_e32 v112, 16, v126
	v_and_b32_e32 v113, 0xffff0000, v126
	v_lshlrev_b32_e32 v114, 16, v127
	global_load_dword v6, v192, s[44:45]
	v_and_b32_e32 v115, 0xffff0000, v127
	v_mul_f32_e32 v120, 0xbfb8aa3b, v112
	v_mul_f32_e32 v121, 0xbfb8aa3b, v113
	v_mul_f32_e32 v122, 0xbfb8aa3b, v114
	v_mul_f32_e32 v123, 0xbfb8aa3b, v115
	v_exp_f32_e32 v120, v120
	global_load_dword v116, v192, s[46:47]
	v_exp_f32_e32 v121, v121
	v_exp_f32_e32 v122, v122
	v_exp_f32_e32 v123, v123
	v_add_f32_e32 v120, 1.0, v120
	v_add_f32_e32 v121, 1.0, v121
	v_add_f32_e32 v122, 1.0, v122
	global_load_dword v117, v193, s[46:47]
	v_add_f32_e32 v123, 1.0, v123
	v_rcp_f32_e32 v120, v120
	v_rcp_f32_e32 v121, v121
	v_rcp_f32_e32 v122, v122
	v_rcp_f32_e32 v123, v123
	v_mul_f32_e32 v112, v120, v112
	s_add_u32 s66, s54, 3
	s_cmp_lt_u32 s66, s39
	s_cselect_b32 s74, 0xc0000, 0
	s_cselect_b32 s75, 0x280000, 0
	s_cselect_b32 s76, 0x4000, 0
	s_add_u32 s40, s40, s74
	s_addc_u32 s41, s41, 0
	s_add_u32 s42, s42, s75
	s_addc_u32 s43, s43, 0
	s_add_u32 s44, s44, s76
	s_addc_u32 s45, s45, 0
	s_add_u32 s46, s46, s76
	s_addc_u32 s47, s47, 0
	v_mul_f32_e32 v113, v121, v113
	v_mul_f32_e32 v114, v122, v114
	s_waitcnt vmcnt(10)
; __device__ __forceinline__ void phase_ssd(const Params& P, int seg, unsigned char* smem) {
;     ...
;             bf16x8 cf[4];
; #pragma unroll
;             for (int k = 0; k < 4; ++k) cf[k] = *(const bf16x8*)(sb + T_CS + (lt * 16 + fr) * 272 + (k * 32 + fq * 8) * 2);
;             f32x4 yo = {0.f, 0.f, 0.f, 0.f};
; #pragma unroll
;             for (int k = 0; k < 4; ++k) { const bf16x8 bb = *(const bf16x8*)((const unsigned char*)StR + (pt * 16 + fr) * 272 + (k * 32 + fq * 8) * 2); yo = mfma16(cf[k], bb, yo); }
; { const f32x4 a4 = *(const f32x4*)(acP + lt * 16 + fq * 4);
; #pragma unroll
;               for (int j = 0; j < 4; ++j) yo[j] *= __expf(a4[j]); }
;             const float acl_fr = acP[lt * 16 + fr]; const int lrow = lt * 16 + fr;
; #pragma unroll
;             for (int t = 0; t < 2; ++t) {
;                 if (2 * t <= lt) {
;                     v2u xb0, xb1;
;                     { const unsigned a0 = lds0 + par * T_BUF + T_XD + (32 * t + 4 * fq + tq) * 80 + (pt * 16 + 4 * tp) * 2, a1 = a0 + 16 * 80; TR_ISSUE(xb0, a0); TR_ISSUE(xb1, a1); }
;                     float m[8];
;                     { f32x4 s0 = {0.f, 0.f, 0.f, 0.f}, s1 = {0.f, 0.f, 0.f, 0.f};
; #pragma unroll
;                       for (int k = 0; k < 4; ++k) { const bf16x8 bf0 = *(const bf16x8*)(sb + T_BS + ((2 * t) * 16 + fr) * 272 + (k * 32 + fq * 8) * 2), bf1 = *(const bf16x8*)(sb + T_BS + ((2 * t + 1) * 16 + fr) * 272 + (k * 32 + fq * 8) * 2);
;                           s0 = mfma16(bf0, cf[k], s0); s1 = mfma16(bf1, cf[k], s1); }
;                       const f32x4 a0 = *(const f32x4*)(acP + (2 * t) * 16 + fq * 4), a1 = *(const f32x4*)(acP + (2 * t + 1) * 16 + fq * 4);
; #pragma unroll
;                       for (int j = 0; j < 4; ++j) { const int si0 = (2 * t) * 16 + fq * 4 + j, si1 = si0 + 16;
;                           const float e0 = s0[j] * __expf(fminf(acl_fr - a0[j], 0.f)), e1 = s1[j] * __expf(fminf(acl_fr - a1[j], 0.f));
;                           m[j] = (si0 <= lrow) ? e0 : 0.f; m[4 + j] = (si1 <= lrow) ? e1 : 0.f; } }
;                     v4u mp; mp.x = cvt_pk_bf16(m[0], m[1]); mp.y = cvt_pk_bf16(m[2], m[3]); mp.z = cvt_pk_bf16(m[4], m[5]); mp.w = cvt_pk_bf16(m[6], m[7]);
;                     asm volatile("s_waitcnt lgkmcnt(0)" : "+v"(xb0), "+v"(xb1) :: "memory");
;                     yo = mfma16(__builtin_bit_cast(bf16x8, mp), mk8(xb0, xb1), yo);
	v_mul_f32_e32 v115, v123, v115
	v_lshlrev_b32_e32 v120, 16, v124
	ds_write_b128 v197, v[140:143]
	v_and_b32_e32 v121, 0xffff0000, v124
	ds_write_b128 v197, v[144:147] offset:8192
	v_lshlrev_b32_e32 v122, 16, v125
	v_and_b32_e32 v123, 0xffff0000, v125
	v_sub_f32_e32 v188, v153, v152
	v_sub_f32_e32 v156, v167, v96
	v_sub_f32_e32 v157, v167, v97
	v_mul_f32_e32 v188, 0x3fb8aa3b, v188
	v_sub_f32_e32 v158, v167, v98
	v_sub_f32_e32 v159, v167, v99
	v_exp_f32_e32 v188, v188
	v_exp_f32_e32 v156, v156
	v_exp_f32_e32 v157, v157
	v_lshlrev_b32_e32 v184, 16, v148
	v_exp_f32_e32 v158, v158
	v_exp_f32_e32 v159, v159
	v_and_b32_e32 v185, 0xffff0000, v148
	v_mul_f32_e32 v156, v48, v156
	v_mul_f32_e32 v157, v49, v157
	v_lshlrev_b32_e32 v186, 16, v149
	v_mul_f32_e32 v158, v50, v158
	v_mul_f32_e32 v159, v51, v159
	v_and_b32_e32 v187, 0xffff0000, v149
	v_sub_f32_e32 v160, v167, v100
	v_sub_f32_e32 v161, v167, v101
	v_mul_f32_e32 v184, v184, v118
	v_sub_f32_e32 v162, v167, v102
	v_sub_f32_e32 v163, v167, v103
	v_mul_f32_e32 v185, v185, v118
	v_exp_f32_e32 v160, v160
	v_exp_f32_e32 v161, v161
	v_mul_f32_e32 v186, v186, v118
	v_exp_f32_e32 v162, v162
	v_exp_f32_e32 v163, v163
	v_mul_f32_e32 v187, v187, v118
	v_mul_f32_e32 v160, v52, v160
	v_mul_f32_e32 v161, v53, v161
	v_cvt_pk_bf16_f32 v190, v184, v185
	v_mul_f32_e32 v162, v54, v162
	v_mul_f32_e32 v163, v55, v163
	v_cvt_pk_bf16_f32 v191, v186, v187
	v_cvt_pk_bf16_f32 v128, v156, v157
	ds_write_b64 v199, v[190:191] offset:32768
	v_cvt_pk_bf16_f32 v129, v158, v159
	v_cvt_pk_bf16_f32 v130, v160, v161
	v_mul_f32_e32 v184, v184, v188
	v_cvt_pk_bf16_f32 v131, v162, v163
	s_waitcnt lgkmcnt(9)
	s_nop 0
	v_mfma_f32_16x16x32_bf16 v[24:27], v[56:59], v[128:131], v[24:27]
	v_mul_f32_e32 v185, v185, v188
	ds_read_b128 v[96:99], v216 offset:128
	s_waitcnt lgkmcnt(9)
	v_mfma_f32_16x16x32_bf16 v[48:51], v[64:67], v[28:31], 0
	v_mul_f32_e32 v186, v186, v188
	s_waitcnt lgkmcnt(8)
	v_mfma_f32_16x16x32_bf16 v[48:51], v[68:71], v[32:35], v[48:51]
	s_waitcnt lgkmcnt(7)
	v_mfma_f32_16x16x32_bf16 v[48:51], v[72:75], v[40:43], v[48:51]
	v_mul_f32_e32 v187, v187, v188
	s_waitcnt lgkmcnt(6)
	v_mfma_f32_16x16x32_bf16 v[48:51], v[76:79], v[44:47], v[48:51]
	s_waitcnt lgkmcnt(0)
	v_sub_f32_e32 v156, v167, v96
	v_cvt_pk_bf16_f32 v164, v184, v185
	v_sub_f32_e32 v157, v167, v97
	v_sub_f32_e32 v158, v167, v98
	v_cvt_pk_bf16_f32 v165, v186, v187
	v_sub_f32_e32 v159, v167, v99
	v_exp_f32_e32 v156, v156
	ds_write_b64 v199, v[164:165] offset:37888
	v_exp_f32_e32 v157, v157
	v_exp_f32_e32 v158, v158
	ds_write_b64 v201, v[148:149] offset:43008
	v_exp_f32_e32 v159, v159
	v_mul_f32_e32 v156, v48, v156
	ds_write_b64 v201, v[150:151] offset:47616
	v_mul_f32_e32 v157, v49, v157
	v_mul_f32_e32 v158, v50, v158
	v_mul_f32_e32 v189, 0x3fb8aa3b, v152
	v_mul_f32_e32 v159, v51, v159
	v_cndmask_b32_e64 v156, 0, v156, s[14:15]
	ds_write_b32 v202, v189 offset:256
	v_cndmask_b32_e64 v157, 0, v157, s[16:17]
	v_cndmask_b32_e64 v158, 0, v158, s[22:23]
	v_mul_f32_e32 v166, 0x3fb8aa3b, v153
	v_cndmask_b32_e64 v159, 0, v159, s[34:35]
	v_cvt_pk_bf16_f32 v128, v156, v157
	v_exp_f32_e32 v166, v166
	v_cvt_pk_bf16_f32 v129, v158, v159
	v_mov_b32_e32 v130, 0
	v_mov_b32_e32 v131, 0
	s_nop 1
	v_mfma_f32_16x16x32_bf16 v[24:27], v[60:63], v[128:131], v[24:27]
	s_mul_i32 s65, s56, 0x2000
	s_add_u32 s65, s65, 0x304f1000
	s_add_u32 s48, s0, s65
	s_addc_u32 s49, s1, 0
	s_nop 3
	v_fma_f32 v156, s61, v120, v24
	v_fma_f32 v157, s61, v121, v25
	v_fma_f32 v158, s61, v122, v26
	v_fma_f32 v159, s61, v123, v27
	v_mul_f32_e32 v156, v156, v112
	v_mul_f32_e32 v157, v157, v113
	v_mul_f32_e32 v158, v158, v114
	v_mul_f32_e32 v159, v159, v115
	v_cvt_pk_bf16_f32 v154, v156, v157
	v_cvt_pk_bf16_f32 v155, v158, v159
	global_store_dwordx2 v194, v[154:155], s[48:49]
	s_add_u32 s65, s54, 1
	s_sub_u32 s65, s65, s60
	s_lshl_b32 s65, s65, 6
	s_add_u32 s56, s65, s20
	s_waitcnt lgkmcnt(0)
	s_barrier
	s_mov_b32 s80, s77
	s_mov_b32 s77, s78
	s_mov_b32 s78, s79
	s_mov_b32 s79, s80
	s_add_u32 s54, s54, 1
	s_cmp_ge_u32 s54, s39
	s_cbranch_scc1 .Lssd_done
	v_add_u32_e32 v229, s77, v203
	v_add_u32_e32 v230, s77, v204
	v_add_u32_e32 v231, s77, v205
	v_add_u32_e32 v232, s77, v206
	ds_read_b128 v[28:31], v207 offset:8192
	ds_read_b128 v[32:35], v208 offset:8192
	ds_read_b128 v[40:43], v209 offset:8192
	ds_read_b128 v[44:47], v210 offset:8192
	ds_read_b128 v[48:51], v211 offset:8192
	ds_read_b128 v[52:55], v212 offset:8192
	ds_read_b128 v[56:59], v213 offset:8192
	ds_read_b128 v[60:63], v214 offset:8192
	ds_read_b32 v167, v215 offset:384
	ds_read_b128 v[64:67], v229
	ds_read_b128 v[68:71], v230
	ds_read_b128 v[72:75], v231
	ds_read_b128 v[76:79], v232
	ds_read_b128 v[80:83], v229 offset:4096
	ds_read_b128 v[84:87], v230 offset:4096
	global_load_dwordx4 v[140:143], v169, s[40:41] offset:2048
	s_waitcnt lgkmcnt(11)
	ds_read_b128 v[88:91], v231 offset:4096
	ds_read_b128 v[92:95], v232 offset:4096
	ds_read_b128 v[96:99], v216 offset:256
	ds_read_b128 v[100:103], v216 offset:320
	s_waitcnt lgkmcnt(11)
	ds_read_b64 v[124:125], v220 offset:45312
	global_load_dwordx4 v[144:147], v170, s[40:41] offset:2048
	ds_read_b64 v[126:127], v220 offset:49920
	v_mfma_f32_16x16x32_bf16 v[24:27], v[48:51], v[28:31], 0
	v_mfma_f32_16x16x32_bf16 v[24:27], v[52:55], v[32:35], v[24:27]
	v_mfma_f32_16x16x32_bf16 v[24:27], v[56:59], v[40:43], v[24:27]
	v_mfma_f32_16x16x32_bf16 v[24:27], v[60:63], v[44:47], v[24:27]
	ds_read_b64_tr_b16 v[56:57], v218 offset:32768
	s_add_u32 m0, s79, s81
	s_nop 0
	global_load_lds_dwordx4 v235, s[40:41]
	ds_read_b64_tr_b16 v[58:59], v218 offset:34048
	s_waitcnt lgkmcnt(13)
	v_mfma_f32_16x16x32_bf16 v[48:51], v[64:67], v[28:31], 0
	s_waitcnt lgkmcnt(9)
; __device__ __forceinline__ void phase_ssd(const Params& P, int seg, unsigned char* smem) {
;     ...
;               for (int i = 0; i < 2; ++i) { const int q = tid + 512 * i, l = q >> 4, c8 = q & 15; *(v4u*)(sb + T_CS + l * 272 + c8 * 16) = R.Cr[i]; *(v4u*)(sb + T_BS + l * 272 + c8 * 16) = R.Br[i]; }
;               const int l = tid >> 3, p4 = (tid & 7) * 4;
;               const float x0 = bflo(R.Xr.x) * R.dtl, x1 = bfhi(R.Xr.x) * R.dtl, x2 = bflo(R.Xr.y) * R.dtl, x3 = bfhi(R.Xr.y) * R.dtl;
;               v2u d; d.x = cvt_pk_bf16(x0, x1); d.y = cvt_pk_bf16(x2, x3); *(v2u*)(sb + T_XD + l * 80 + p4 * 2) = d;
;               v2u e; e.x = cvt_pk_bf16(x0 * e2, x1 * e2); e.y = cvt_pk_bf16(x2 * e2, x3 * e2); *(v2u*)(sb + T_XE + l * 80 + p4 * 2) = e;
;               *(v2u*)(sb + T_XS + l * 64 + p4 * 2) = R.Xr; *(v2u*)(sb + T_ZS + l * 64 + p4 * 2) = R.Zr;
;               if (w == 0) acP[lane] = R.aclane; }
;             BAR_LDS();
;             if (ci + 2 < nchunks) load_chunk(ci + 2, R);
;             bf16x8 cf[4];
; #pragma unroll
;             for (int k = 0; k < 4; ++k) cf[k] = *(const bf16x8*)(sb + T_CS + (lt * 16 + fr) * 272 + (k * 32 + fq * 8) * 2);
;             f32x4 yo = {0.f, 0.f, 0.f, 0.f};
; #pragma unroll
;             for (int k = 0; k < 4; ++k) { const bf16x8 bb = *(const bf16x8*)((const unsigned char*)StR + (pt * 16 + fr) * 272 + (k * 32 + fq * 8) * 2); yo = mfma16(cf[k], bb, yo); }
; { const f32x4 a4 = *(const f32x4*)(acP + lt * 16 + fq * 4);
; #pragma unroll
;               for (int j = 0; j < 4; ++j) yo[j] *= __expf(a4[j]); }
;             const float acl_fr = acP[lt * 16 + fr]; const int lrow = lt * 16 + fr;
; #pragma unroll
;             for (int t = 0; t < 2; ++t) {
;                 if (2 * t <= lt) {
;                     v2u xb0, xb1;
;                     { const unsigned a0 = lds0 + par * T_BUF + T_XD + (32 * t + 4 * fq + tq) * 80 + (pt * 16 + 4 * tp) * 2, a1 = a0 + 16 * 80; TR_ISSUE(xb0, a0); TR_ISSUE(xb1, a1); }
;                     float m[8];
;                     { f32x4 s0 = {0.f, 0.f, 0.f, 0.f}, s1 = {0.f, 0.f, 0.f, 0.f};
; #pragma unroll
;                       for (int k = 0; k < 4; ++k) { const bf16x8 bf0 = *(const bf16x8*)(sb + T_BS + ((2 * t) * 16 + fr) * 272 + (k * 32 + fq * 8) * 2), bf1 = *(const bf16x8*)(sb + T_BS + ((2 * t + 1) * 16 + fr) * 272 + (k * 32 + fq * 8) * 2);
	v_mfma_f32_16x16x32_bf16 v[52:55], v[80:83], v[28:31], 0
	v_mfma_f32_16x16x32_bf16 v[48:51], v[68:71], v[32:35], v[48:51]
	s_waitcnt lgkmcnt(8)
	v_mfma_f32_16x16x32_bf16 v[52:55], v[84:87], v[32:35], v[52:55]
	v_mfma_f32_16x16x32_bf16 v[48:51], v[72:75], v[40:43], v[48:51]
	s_add_u32 m0, m0, 0x2000
	s_nop 0
	global_load_lds_dwordx4 v236, s[40:41]
	s_waitcnt lgkmcnt(7)
	v_mfma_f32_16x16x32_bf16 v[52:55], v[88:91], v[40:43], v[52:55]
	v_mfma_f32_16x16x32_bf16 v[48:51], v[76:79], v[44:47], v[48:51]
	s_waitcnt lgkmcnt(6)
	v_mfma_f32_16x16x32_bf16 v[52:55], v[92:95], v[44:47], v[52:55]
	ds_read_b128 v[64:67], v229 offset:8192
	ds_read_b128 v[68:71], v230 offset:8192
	ds_read_b128 v[72:75], v231 offset:8192
	global_load_dwordx2 v[148:149], v171, s[40:41]
	ds_read_b128 v[76:79], v232 offset:8192
	ds_read_b64_tr_b16 v[60:61], v218 offset:35328
	ds_read_b64_tr_b16 v[62:63], v218 offset:36608
	v_exp_f32_e32 v168, v167
	s_nop 0
	v_mul_f32_e32 v24, v24, v168
	global_load_dwordx2 v[150:151], v174, s[42:43] nt
	v_mul_f32_e32 v25, v25, v168
	v_mul_f32_e32 v26, v26, v168
	v_mul_f32_e32 v27, v27, v168
	s_waitcnt lgkmcnt(8)
	v_lshlrev_b32_e32 v112, 16, v126
	v_and_b32_e32 v113, 0xffff0000, v126
	v_lshlrev_b32_e32 v114, 16, v127
	global_load_dword v118, v192, s[44:45]
	v_and_b32_e32 v115, 0xffff0000, v127
	v_mul_f32_e32 v120, 0xbfb8aa3b, v112
	v_mul_f32_e32 v121, 0xbfb8aa3b, v113
	v_mul_f32_e32 v122, 0xbfb8aa3b, v114
	v_mul_f32_e32 v123, 0xbfb8aa3b, v115
	v_exp_f32_e32 v120, v120
	global_load_dword v152, v192, s[46:47]
	v_exp_f32_e32 v121, v121
	v_exp_f32_e32 v122, v122
	v_exp_f32_e32 v123, v123
	v_add_f32_e32 v120, 1.0, v120
	v_add_f32_e32 v121, 1.0, v121
	v_add_f32_e32 v122, 1.0, v122
	global_load_dword v153, v193, s[46:47]
	v_add_f32_e32 v123, 1.0, v123
	v_rcp_f32_e32 v120, v120
	v_rcp_f32_e32 v121, v121
	v_rcp_f32_e32 v122, v122
	v_rcp_f32_e32 v123, v123
	v_mul_f32_e32 v112, v120, v112
	s_add_u32 s66, s54, 3
	s_cmp_lt_u32 s66, s39
	s_cselect_b32 s74, 0xc0000, 0
	s_cselect_b32 s75, 0x280000, 0
	s_cselect_b32 s76, 0x4000, 0
	s_add_u32 s40, s40, s74
	s_addc_u32 s41, s41, 0
	s_add_u32 s42, s42, s75
	s_addc_u32 s43, s43, 0
	s_add_u32 s44, s44, s76
	s_addc_u32 s45, s45, 0
	s_add_u32 s46, s46, s76
	s_addc_u32 s47, s47, 0
	v_mul_f32_e32 v113, v121, v113
	v_mul_f32_e32 v114, v122, v114
	s_waitcnt vmcnt(10)
	v_mul_f32_e32 v115, v123, v115
	v_lshlrev_b32_e32 v120, 16, v124
	ds_write_b128 v196, v[132:135]
	v_and_b32_e32 v121, 0xffff0000, v124
	ds_write_b128 v196, v[136:139] offset:8192
	v_lshlrev_b32_e32 v122, 16, v125
	v_and_b32_e32 v123, 0xffff0000, v125
	v_sub_f32_e32 v188, v117, v116
	v_sub_f32_e32 v156, v167, v96
	v_sub_f32_e32 v157, v167, v97
	v_mul_f32_e32 v188, 0x3fb8aa3b, v188
	v_sub_f32_e32 v158, v167, v98
	v_sub_f32_e32 v159, v167, v99
	v_exp_f32_e32 v188, v188
	v_exp_f32_e32 v156, v156
	v_exp_f32_e32 v157, v157
	v_lshlrev_b32_e32 v184, 16, v4
	v_exp_f32_e32 v158, v158
	v_exp_f32_e32 v159, v159
	v_and_b32_e32 v185, 0xffff0000, v4
	v_mul_f32_e32 v156, v48, v156
	v_mul_f32_e32 v157, v49, v157
	v_lshlrev_b32_e32 v186, 16, v5
	v_mul_f32_e32 v158, v50, v158
	v_mul_f32_e32 v159, v51, v159
	v_and_b32_e32 v187, 0xffff0000, v5
	v_sub_f32_e32 v160, v167, v100
	v_sub_f32_e32 v161, v167, v101
	v_mul_f32_e32 v184, v184, v6
	v_sub_f32_e32 v162, v167, v102
	v_sub_f32_e32 v163, v167, v103
	v_mul_f32_e32 v185, v185, v6
	v_exp_f32_e32 v160, v160
	v_exp_f32_e32 v161, v161
	v_mul_f32_e32 v186, v186, v6
	v_exp_f32_e32 v162, v162
	v_exp_f32_e32 v163, v163
	v_mul_f32_e32 v187, v187, v6
	v_mul_f32_e32 v160, v52, v160
	v_mul_f32_e32 v161, v53, v161
	v_cvt_pk_bf16_f32 v190, v184, v185
	v_mul_f32_e32 v162, v54, v162
	v_mul_f32_e32 v163, v55, v163
	v_cvt_pk_bf16_f32 v191, v186, v187
	v_cvt_pk_bf16_f32 v128, v156, v157
	ds_write_b64 v198, v[190:191] offset:32768
	v_cvt_pk_bf16_f32 v129, v158, v159
	v_cvt_pk_bf16_f32 v130, v160, v161
	v_mul_f32_e32 v184, v184, v188
	v_cvt_pk_bf16_f32 v131, v162, v163
	s_waitcnt lgkmcnt(9)
	s_nop 0
	v_mfma_f32_16x16x32_bf16 v[24:27], v[56:59], v[128:131], v[24:27]
	v_mul_f32_e32 v185, v185, v188
	ds_read_b128 v[96:99], v216 offset:384
	s_waitcnt lgkmcnt(9)
	v_mfma_f32_16x16x32_bf16 v[48:51], v[64:67], v[28:31], 0
	v_mul_f32_e32 v186, v186, v188
	s_waitcnt lgkmcnt(8)
	v_mfma_f32_16x16x32_bf16 v[48:51], v[68:71], v[32:35], v[48:51]
	s_waitcnt lgkmcnt(7)
	v_mfma_f32_16x16x32_bf16 v[48:51], v[72:75], v[40:43], v[48:51]
	v_mul_f32_e32 v187, v187, v188
	s_waitcnt lgkmcnt(6)
	v_mfma_f32_16x16x32_bf16 v[48:51], v[76:79], v[44:47], v[48:51]
	s_waitcnt lgkmcnt(0)
	v_sub_f32_e32 v156, v167, v96
	v_cvt_pk_bf16_f32 v164, v184, v185
	v_sub_f32_e32 v157, v167, v97
	v_sub_f32_e32 v158, v167, v98
	v_cvt_pk_bf16_f32 v165, v186, v187
	v_sub_f32_e32 v159, v167, v99
	v_exp_f32_e32 v156, v156
	ds_write_b64 v198, v[164:165] offset:37888
	v_exp_f32_e32 v157, v157
	v_exp_f32_e32 v158, v158
	ds_write_b64 v200, v[4:5] offset:43008
	v_exp_f32_e32 v159, v159
	v_mul_f32_e32 v156, v48, v156
	ds_write_b64 v200, v[36:37] offset:47616
	v_mul_f32_e32 v157, v49, v157
	v_mul_f32_e32 v158, v50, v158
	v_mul_f32_e32 v189, 0x3fb8aa3b, v116
	v_mul_f32_e32 v159, v51, v159
	v_cndmask_b32_e64 v156, 0, v156, s[14:15]
	ds_write_b32 v202, v189
	v_cndmask_b32_e64 v157, 0, v157, s[16:17]
	v_cndmask_b32_e64 v158, 0, v158, s[22:23]
	v_mul_f32_e32 v166, 0x3fb8aa3b, v117
	v_cndmask_b32_e64 v159, 0, v159, s[34:35]
	v_cvt_pk_bf16_f32 v128, v156, v157
	v_exp_f32_e32 v166, v166
	v_cvt_pk_bf16_f32 v129, v158, v159
	v_mov_b32_e32 v130, 0
	v_mov_b32_e32 v131, 0
	s_nop 1
	v_mfma_f32_16x16x32_bf16 v[24:27], v[60:63], v[128:131], v[24:27]
	s_mul_i32 s65, s56, 0x2000
	s_add_u32 s65, s65, 0x304f1000
	s_add_u32 s48, s0, s65
	s_addc_u32 s49, s1, 0
	s_nop 3
	v_fma_f32 v156, s61, v120, v24
	v_fma_f32 v157, s61, v121, v25
	v_fma_f32 v158, s61, v122, v26
	v_fma_f32 v159, s61, v123, v27
	v_mul_f32_e32 v156, v156, v112
	v_mul_f32_e32 v157, v157, v113
	v_mul_f32_e32 v158, v158, v114
	v_mul_f32_e32 v159, v159, v115
	v_cvt_pk_bf16_f32 v154, v156, v157
	v_cvt_pk_bf16_f32 v155, v158, v159
	global_store_dwordx2 v194, v[154:155], s[48:49]
	s_add_u32 s65, s54, 1
	s_sub_u32 s65, s65, s60
	s_lshl_b32 s65, s65, 6
	s_add_u32 s56, s65, s20
	s_waitcnt lgkmcnt(0)
	s_barrier
	s_mov_b32 s80, s77
	s_mov_b32 s77, s78
	s_mov_b32 s78, s79
	s_mov_b32 s79, s80
	s_add_u32 s54, s54, 1
	s_cmp_lt_u32 s54, s39
	s_cbranch_scc1 .Lssd_loop2
	s_branch .Lssd_done
; __device__ __forceinline__ void phase_ssd(const Params& P, int seg, unsigned char* smem) {
;     ...
;             bf16x8 cf[4];
; #pragma unroll
;             for (int k = 0; k < 4; ++k) cf[k] = *(const bf16x8*)(sb + T_CS + (lt * 16 + fr) * 272 + (k * 32 + fq * 8) * 2);
;             f32x4 yo = {0.f, 0.f, 0.f, 0.f};
; #pragma unroll
;             for (int k = 0; k < 4; ++k) { const bf16x8 bb = *(const bf16x8*)((const unsigned char*)StR + (pt * 16 + fr) * 272 + (k * 32 + fq * 8) * 2); yo = mfma16(cf[k], bb, yo); }
; { const f32x4 a4 = *(const f32x4*)(acP + lt * 16 + fq * 4);
; #pragma unroll
;               for (int j = 0; j < 4; ++j) yo[j] *= __expf(a4[j]); }
;             const float acl_fr = acP[lt * 16 + fr]; const int lrow = lt * 16 + fr;
; #pragma unroll
;             for (int t = 0; t < 2; ++t) {
;                 if (2 * t <= lt) {
;                     v2u xb0, xb1;
;                     { const unsigned a0 = lds0 + par * T_BUF + T_XD + (32 * t + 4 * fq + tq) * 80 + (pt * 16 + 4 * tp) * 2, a1 = a0 + 16 * 80; TR_ISSUE(xb0, a0); TR_ISSUE(xb1, a1); }
;                     float m[8];
;                     { f32x4 s0 = {0.f, 0.f, 0.f, 0.f}, s1 = {0.f, 0.f, 0.f, 0.f};
; #pragma unroll
;                       for (int k = 0; k < 4; ++k) { const bf16x8 bf0 = *(const bf16x8*)(sb + T_BS + ((2 * t) * 16 + fr) * 272 + (k * 32 + fq * 8) * 2), bf1 = *(const bf16x8*)(sb + T_BS + ((2 * t + 1) * 16 + fr) * 272 + (k * 32 + fq * 8) * 2);
;                           s0 = mfma16(bf0, cf[k], s0); s1 = mfma16(bf1, cf[k], s1); }
;                       const f32x4 a0 = *(const f32x4*)(acP + (2 * t) * 16 + fq * 4), a1 = *(const f32x4*)(acP + (2 * t + 1) * 16 + fq * 4);
; #pragma unroll
;                       for (int j = 0; j < 4; ++j) { const int si0 = (2 * t) * 16 + fq * 4 + j, si1 = si0 + 16;
;                           const float e0 = s0[j] * __expf(fminf(acl_fr - a0[j], 0.f)), e1 = s1[j] * __expf(fminf(acl_fr - a1[j], 0.f));
;                           m[j] = (si0 <= lrow) ? e0 : 0.f; m[4 + j] = (si1 <= lrow) ? e1 : 0.f; } }
;                     v4u mp; mp.x = cvt_pk_bf16(m[0], m[1]); mp.y = cvt_pk_bf16(m[2], m[3]); mp.z = cvt_pk_bf16(m[4], m[5]); mp.w = cvt_pk_bf16(m[6], m[7]);
;                     asm volatile("s_waitcnt lgkmcnt(0)" : "+v"(xb0), "+v"(xb1) :: "memory");
;                     yo = mfma16(__builtin_bit_cast(bf16x8, mp), mk8(xb0, xb1), yo);
.Lssd_loop3:
	v_add_u32_e32 v229, s77, v203
	v_add_u32_e32 v230, s77, v204
	v_add_u32_e32 v231, s77, v205
	v_add_u32_e32 v232, s77, v206
	ds_read_b128 v[28:31], v203 offset:12288
	ds_read_b128 v[32:35], v204 offset:12288
	ds_read_b128 v[40:43], v205 offset:12288
	ds_read_b128 v[44:47], v206 offset:12288
	ds_read_b128 v[48:51], v211
	ds_read_b128 v[52:55], v212
	ds_read_b128 v[56:59], v213
	ds_read_b128 v[60:63], v214
	ds_read_b32 v167, v215 offset:192
	ds_read_b128 v[64:67], v229
	ds_read_b128 v[68:71], v230
	ds_read_b128 v[72:75], v231
	ds_read_b128 v[76:79], v232
	ds_read_b128 v[80:83], v229 offset:4096
	ds_read_b128 v[84:87], v230 offset:4096
	global_load_dwordx4 v[132:135], v169, s[40:41] offset:2048
	s_waitcnt lgkmcnt(11)
	ds_read_b128 v[88:91], v231 offset:4096
	ds_read_b128 v[92:95], v232 offset:4096
	ds_read_b128 v[96:99], v216
	ds_read_b128 v[100:103], v216 offset:64
	s_waitcnt lgkmcnt(11)
	ds_read_b64 v[124:125], v219 offset:46464
	ds_read_b64 v[126:127], v219 offset:51072
	global_load_dwordx4 v[136:139], v170, s[40:41] offset:2048
	v_mfma_f32_16x16x32_bf16 v[24:27], v[48:51], v[28:31], 0
	v_mfma_f32_16x16x32_bf16 v[24:27], v[52:55], v[32:35], v[24:27]
	v_mfma_f32_16x16x32_bf16 v[24:27], v[56:59], v[40:43], v[24:27]
	v_mfma_f32_16x16x32_bf16 v[24:27], v[60:63], v[44:47], v[24:27]
	ds_read_b64_tr_b16 v[56:57], v217 offset:32768
	ds_read_b64_tr_b16 v[58:59], v217 offset:34048
	s_waitcnt lgkmcnt(13)
	v_mfma_f32_16x16x32_bf16 v[48:51], v[64:67], v[28:31], 0
	s_add_u32 m0, s79, s81
	s_nop 0
	global_load_lds_dwordx4 v235, s[40:41]
	s_waitcnt lgkmcnt(9)
	v_mfma_f32_16x16x32_bf16 v[52:55], v[80:83], v[28:31], 0
	v_mfma_f32_16x16x32_bf16 v[48:51], v[68:71], v[32:35], v[48:51]
	s_waitcnt lgkmcnt(8)
	v_mfma_f32_16x16x32_bf16 v[52:55], v[84:87], v[32:35], v[52:55]
	v_mfma_f32_16x16x32_bf16 v[48:51], v[72:75], v[40:43], v[48:51]
	s_waitcnt lgkmcnt(7)
	v_mfma_f32_16x16x32_bf16 v[52:55], v[88:91], v[40:43], v[52:55]
	v_mfma_f32_16x16x32_bf16 v[48:51], v[76:79], v[44:47], v[48:51]
	s_waitcnt lgkmcnt(6)
	v_mfma_f32_16x16x32_bf16 v[52:55], v[92:95], v[44:47], v[52:55]
	s_add_u32 m0, m0, 0x2000
	s_nop 0
	global_load_lds_dwordx4 v236, s[40:41]
	ds_read_b128 v[64:67], v229 offset:8192
	ds_read_b128 v[68:71], v230 offset:8192
	ds_read_b128 v[72:75], v231 offset:8192
	ds_read_b128 v[76:79], v232 offset:8192
	ds_read_b128 v[80:83], v229 offset:12288
	ds_read_b128 v[84:87], v230 offset:12288
	ds_read_b128 v[88:91], v231 offset:12288
	global_load_dwordx2 v[4:5], v171, s[40:41]
	ds_read_b128 v[92:95], v232 offset:12288
	ds_read_b64_tr_b16 v[60:61], v217 offset:35328
	s_waitcnt lgkmcnt(11)
	ds_read_b64_tr_b16 v[62:63], v217 offset:36608
	v_exp_f32_e32 v168, v167
	s_nop 0
	v_mul_f32_e32 v24, v24, v168
	v_mul_f32_e32 v25, v25, v168
	v_mul_f32_e32 v26, v26, v168
	global_load_dwordx2 v[36:37], v174, s[42:43] nt
	v_mul_f32_e32 v27, v27, v168
	v_lshlrev_b32_e32 v112, 16, v126
	v_and_b32_e32 v113, 0xffff0000, v126
	v_lshlrev_b32_e32 v114, 16, v127
	v_and_b32_e32 v115, 0xffff0000, v127
	v_mul_f32_e32 v120, 0xbfb8aa3b, v112
	v_mul_f32_e32 v121, 0xbfb8aa3b, v113
	global_load_dword v6, v192, s[44:45]
	v_mul_f32_e32 v122, 0xbfb8aa3b, v114
	v_mul_f32_e32 v123, 0xbfb8aa3b, v115
	v_exp_f32_e32 v120, v120
	v_exp_f32_e32 v121, v121
	v_exp_f32_e32 v122, v122
	v_exp_f32_e32 v123, v123
	v_add_f32_e32 v120, 1.0, v120
	global_load_dword v116, v192, s[46:47]
	v_add_f32_e32 v121, 1.0, v121
	v_add_f32_e32 v122, 1.0, v122
	v_add_f32_e32 v123, 1.0, v123
	v_rcp_f32_e32 v120, v120
	v_rcp_f32_e32 v121, v121
	v_rcp_f32_e32 v122, v122
	v_rcp_f32_e32 v123, v123
	global_load_dword v117, v193, s[46:47]
	v_mul_f32_e32 v112, v120, v112
	v_mul_f32_e32 v113, v121, v113
	v_mul_f32_e32 v114, v122, v114
	v_mul_f32_e32 v115, v123, v115
	v_lshlrev_b32_e32 v120, 16, v124
	v_and_b32_e32 v121, 0xffff0000, v124
	s_add_u32 s66, s54, 3
	s_cmp_lt_u32 s66, s39
	s_cselect_b32 s74, 0xc0000, 0
	s_cselect_b32 s75, 0x280000, 0
	s_cselect_b32 s76, 0x4000, 0
	s_add_u32 s40, s40, s74
	s_addc_u32 s41, s41, 0
	s_add_u32 s42, s42, s75
	s_addc_u32 s43, s43, 0
	s_add_u32 s44, s44, s76
	s_addc_u32 s45, s45, 0
	s_add_u32 s46, s46, s76
	s_addc_u32 s47, s47, 0
	v_lshlrev_b32_e32 v122, 16, v125
	v_and_b32_e32 v123, 0xffff0000, v125
	v_sub_f32_e32 v156, v167, v96
	s_waitcnt vmcnt(10)
	v_sub_f32_e32 v157, v167, v97
	v_sub_f32_e32 v158, v167, v98
	ds_write_b128 v197, v[140:143]
	v_sub_f32_e32 v159, v167, v99
	v_exp_f32_e32 v156, v156
	ds_write_b128 v197, v[144:147] offset:8192
	v_exp_f32_e32 v157, v157
	v_exp_f32_e32 v158, v158
	v_exp_f32_e32 v159, v159
	v_sub_f32_e32 v188, v153, v152
	v_mul_f32_e32 v156, v48, v156
	v_mul_f32_e32 v157, v49, v157
	v_mul_f32_e32 v188, 0x3fb8aa3b, v188
	v_mul_f32_e32 v158, v50, v158
	v_mul_f32_e32 v159, v51, v159
	v_exp_f32_e32 v188, v188
	v_sub_f32_e32 v160, v167, v100
	v_sub_f32_e32 v161, v167, v101
	v_lshlrev_b32_e32 v184, 16, v148
	v_sub_f32_e32 v162, v167, v102
	v_sub_f32_e32 v163, v167, v103
	v_exp_f32_e32 v160, v160
	v_and_b32_e32 v185, 0xffff0000, v148
	v_exp_f32_e32 v161, v161
	v_exp_f32_e32 v162, v162
	v_lshlrev_b32_e32 v186, 16, v149
	v_exp_f32_e32 v163, v163
	v_mul_f32_e32 v160, v52, v160
	v_and_b32_e32 v187, 0xffff0000, v149
	v_mul_f32_e32 v161, v53, v161
	v_mul_f32_e32 v162, v54, v162
	v_mul_f32_e32 v163, v55, v163
	v_mul_f32_e32 v184, v184, v118
	v_cvt_pk_bf16_f32 v128, v156, v157
	v_cvt_pk_bf16_f32 v129, v158, v159
	v_mul_f32_e32 v185, v185, v118
	v_cvt_pk_bf16_f32 v130, v160, v161
	v_cvt_pk_bf16_f32 v131, v162, v163
	v_mul_f32_e32 v186, v186, v118
	s_waitcnt lgkmcnt(12)
	v_mfma_f32_16x16x32_bf16 v[24:27], v[56:59], v[128:131], v[24:27]
	ds_read_b128 v[96:99], v216 offset:128
	ds_read_b128 v[100:103], v216 offset:192
	v_mul_f32_e32 v187, v187, v118
	s_waitcnt lgkmcnt(13)
; __device__ __forceinline__ void phase_ssd(const Params& P, int seg, unsigned char* smem) {
;     ...
;             bf16x8 cf[4];
; #pragma unroll
;             for (int k = 0; k < 4; ++k) cf[k] = *(const bf16x8*)(sb + T_CS + (lt * 16 + fr) * 272 + (k * 32 + fq * 8) * 2);
;             f32x4 yo = {0.f, 0.f, 0.f, 0.f};
; #pragma unroll
;             for (int k = 0; k < 4; ++k) { const bf16x8 bb = *(const bf16x8*)((const unsigned char*)StR + (pt * 16 + fr) * 272 + (k * 32 + fq * 8) * 2); yo = mfma16(cf[k], bb, yo); }
; { const f32x4 a4 = *(const f32x4*)(acP + lt * 16 + fq * 4);
; #pragma unroll
;               for (int j = 0; j < 4; ++j) yo[j] *= __expf(a4[j]); }
;             const float acl_fr = acP[lt * 16 + fr]; const int lrow = lt * 16 + fr;
; #pragma unroll
;             for (int t = 0; t < 2; ++t) {
;                 if (2 * t <= lt) {
;                     v2u xb0, xb1;
;                     { const unsigned a0 = lds0 + par * T_BUF + T_XD + (32 * t + 4 * fq + tq) * 80 + (pt * 16 + 4 * tp) * 2, a1 = a0 + 16 * 80; TR_ISSUE(xb0, a0); TR_ISSUE(xb1, a1); }
;                     float m[8];
;                     { f32x4 s0 = {0.f, 0.f, 0.f, 0.f}, s1 = {0.f, 0.f, 0.f, 0.f};
; #pragma unroll
;                       for (int k = 0; k < 4; ++k) { const bf16x8 bf0 = *(const bf16x8*)(sb + T_BS + ((2 * t) * 16 + fr) * 272 + (k * 32 + fq * 8) * 2), bf1 = *(const bf16x8*)(sb + T_BS + ((2 * t + 1) * 16 + fr) * 272 + (k * 32 + fq * 8) * 2);
;                           s0 = mfma16(bf0, cf[k], s0); s1 = mfma16(bf1, cf[k], s1); }
;                       const f32x4 a0 = *(const f32x4*)(acP + (2 * t) * 16 + fq * 4), a1 = *(const f32x4*)(acP + (2 * t + 1) * 16 + fq * 4);
; #pragma unroll
;                       for (int j = 0; j < 4; ++j) { const int si0 = (2 * t) * 16 + fq * 4 + j, si1 = si0 + 16;
;                           const float e0 = s0[j] * __expf(fminf(acl_fr - a0[j], 0.f)), e1 = s1[j] * __expf(fminf(acl_fr - a1[j], 0.f));
;                           m[j] = (si0 <= lrow) ? e0 : 0.f; m[4 + j] = (si1 <= lrow) ? e1 : 0.f; } }
;                     v4u mp; mp.x = cvt_pk_bf16(m[0], m[1]); mp.y = cvt_pk_bf16(m[2], m[3]); mp.z = cvt_pk_bf16(m[4], m[5]); mp.w = cvt_pk_bf16(m[6], m[7]);
;                     asm volatile("s_waitcnt lgkmcnt(0)" : "+v"(xb0), "+v"(xb1) :: "memory");
;                     yo = mfma16(__builtin_bit_cast(bf16x8, mp), mk8(xb0, xb1), yo);
	v_mfma_f32_16x16x32_bf16 v[48:51], v[64:67], v[28:31], 0
	s_waitcnt lgkmcnt(9)
	v_mfma_f32_16x16x32_bf16 v[52:55], v[80:83], v[28:31], 0
	v_cvt_pk_bf16_f32 v190, v184, v185
	v_mfma_f32_16x16x32_bf16 v[48:51], v[68:71], v[32:35], v[48:51]
	s_waitcnt lgkmcnt(8)
	v_mfma_f32_16x16x32_bf16 v[52:55], v[84:87], v[32:35], v[52:55]
	v_cvt_pk_bf16_f32 v191, v186, v187
	v_mfma_f32_16x16x32_bf16 v[48:51], v[72:75], v[40:43], v[48:51]
	s_waitcnt lgkmcnt(7)
	v_mfma_f32_16x16x32_bf16 v[52:55], v[88:91], v[40:43], v[52:55]
	ds_write_b64 v199, v[190:191] offset:32768
	v_mfma_f32_16x16x32_bf16 v[48:51], v[76:79], v[44:47], v[48:51]
	s_waitcnt lgkmcnt(7)
	v_mfma_f32_16x16x32_bf16 v[52:55], v[92:95], v[44:47], v[52:55]
	s_waitcnt lgkmcnt(2)
	v_sub_f32_e32 v156, v167, v96
	v_mul_f32_e32 v184, v184, v188
	v_sub_f32_e32 v157, v167, v97
	v_sub_f32_e32 v158, v167, v98
	v_mul_f32_e32 v185, v185, v188
	v_sub_f32_e32 v159, v167, v99
	v_exp_f32_e32 v156, v156
	v_mul_f32_e32 v186, v186, v188
	v_exp_f32_e32 v157, v157
	v_exp_f32_e32 v158, v158
	v_exp_f32_e32 v159, v159
	v_mul_f32_e32 v187, v187, v188
	v_mul_f32_e32 v156, v48, v156
	v_mul_f32_e32 v157, v49, v157
	v_cvt_pk_bf16_f32 v164, v184, v185
	v_mul_f32_e32 v158, v50, v158
	v_mul_f32_e32 v159, v51, v159
	v_cvt_pk_bf16_f32 v165, v186, v187
	s_waitcnt lgkmcnt(1)
	v_sub_f32_e32 v160, v167, v100
	v_sub_f32_e32 v161, v167, v101
	ds_write_b64 v199, v[164:165] offset:37888
	v_sub_f32_e32 v162, v167, v102
	v_sub_f32_e32 v163, v167, v103
	v_exp_f32_e32 v160, v160
	ds_write_b64 v201, v[148:149] offset:43008
	v_exp_f32_e32 v161, v161
	v_exp_f32_e32 v162, v162
	ds_write_b64 v201, v[150:151] offset:47616
	v_exp_f32_e32 v163, v163
	v_mul_f32_e32 v160, v52, v160
	v_mul_f32_e32 v189, 0x3fb8aa3b, v152
	v_mul_f32_e32 v161, v53, v161
	v_mul_f32_e32 v162, v54, v162
	v_mul_f32_e32 v163, v55, v163
	ds_write_b32 v202, v189 offset:256
	v_cndmask_b32_e64 v160, 0, v160, s[14:15]
	v_cndmask_b32_e64 v161, 0, v161, s[16:17]
	v_mul_f32_e32 v166, 0x3fb8aa3b, v153
	v_cndmask_b32_e64 v162, 0, v162, s[22:23]
	v_cndmask_b32_e64 v163, 0, v163, s[34:35]
	v_exp_f32_e32 v166, v166
	v_cvt_pk_bf16_f32 v128, v156, v157
	v_cvt_pk_bf16_f32 v129, v158, v159
	v_cvt_pk_bf16_f32 v130, v160, v161
	v_cvt_pk_bf16_f32 v131, v162, v163
	s_nop 1
	v_mfma_f32_16x16x32_bf16 v[24:27], v[60:63], v[128:131], v[24:27]
	s_mul_i32 s65, s56, 0x2000
	s_add_u32 s65, s65, 0x304f1000
	s_add_u32 s48, s0, s65
	s_addc_u32 s49, s1, 0
	s_nop 3
	v_fma_f32 v156, s61, v120, v24
	v_fma_f32 v157, s61, v121, v25
	v_fma_f32 v158, s61, v122, v26
	v_fma_f32 v159, s61, v123, v27
	v_mul_f32_e32 v156, v156, v112
	v_mul_f32_e32 v157, v157, v113
	v_mul_f32_e32 v158, v158, v114
	v_mul_f32_e32 v159, v159, v115
	v_cvt_pk_bf16_f32 v154, v156, v157
	v_cvt_pk_bf16_f32 v155, v158, v159
	global_store_dwordx2 v194, v[154:155], s[48:49]
	s_add_u32 s65, s54, 1
	s_sub_u32 s65, s65, s60
	s_lshl_b32 s65, s65, 6
	s_add_u32 s56, s65, s20
	s_waitcnt lgkmcnt(0)
	s_barrier
	s_mov_b32 s80, s77
	s_mov_b32 s77, s78
	s_mov_b32 s78, s79
	s_mov_b32 s79, s80
	s_add_u32 s54, s54, 1
	s_cmp_ge_u32 s54, s39
	s_cbranch_scc1 .Lssd_done
	v_add_u32_e32 v229, s77, v203
	v_add_u32_e32 v230, s77, v204
	v_add_u32_e32 v231, s77, v205
	v_add_u32_e32 v232, s77, v206
	ds_read_b128 v[28:31], v207 offset:12288
	ds_read_b128 v[32:35], v208 offset:12288
	ds_read_b128 v[40:43], v209 offset:12288
	ds_read_b128 v[44:47], v210 offset:12288
	ds_read_b128 v[48:51], v211 offset:8192
	ds_read_b128 v[52:55], v212 offset:8192
	ds_read_b128 v[56:59], v213 offset:8192
	ds_read_b128 v[60:63], v214 offset:8192
	ds_read_b32 v167, v215 offset:448
	ds_read_b128 v[64:67], v229
	ds_read_b128 v[68:71], v230
	ds_read_b128 v[72:75], v231
	ds_read_b128 v[76:79], v232
	ds_read_b128 v[80:83], v229 offset:4096
	ds_read_b128 v[84:87], v230 offset:4096
	global_load_dwordx4 v[140:143], v169, s[40:41] offset:2048
	s_waitcnt lgkmcnt(11)
	ds_read_b128 v[88:91], v231 offset:4096
	ds_read_b128 v[92:95], v232 offset:4096
	ds_read_b128 v[96:99], v216 offset:256
	ds_read_b128 v[100:103], v216 offset:320
	s_waitcnt lgkmcnt(11)
	ds_read_b64 v[124:125], v220 offset:46464
	ds_read_b64 v[126:127], v220 offset:51072
	global_load_dwordx4 v[144:147], v170, s[40:41] offset:2048
	v_mfma_f32_16x16x32_bf16 v[24:27], v[48:51], v[28:31], 0
	v_mfma_f32_16x16x32_bf16 v[24:27], v[52:55], v[32:35], v[24:27]
	v_mfma_f32_16x16x32_bf16 v[24:27], v[56:59], v[40:43], v[24:27]
	v_mfma_f32_16x16x32_bf16 v[24:27], v[60:63], v[44:47], v[24:27]
	ds_read_b64_tr_b16 v[56:57], v218 offset:32768
	ds_read_b64_tr_b16 v[58:59], v218 offset:34048
	s_waitcnt lgkmcnt(13)
	v_mfma_f32_16x16x32_bf16 v[48:51], v[64:67], v[28:31], 0
	s_add_u32 m0, s79, s81
	s_nop 0
	global_load_lds_dwordx4 v235, s[40:41]
	s_waitcnt lgkmcnt(9)
	v_mfma_f32_16x16x32_bf16 v[52:55], v[80:83], v[28:31], 0
	v_mfma_f32_16x16x32_bf16 v[48:51], v[68:71], v[32:35], v[48:51]
	s_waitcnt lgkmcnt(8)
	v_mfma_f32_16x16x32_bf16 v[52:55], v[84:87], v[32:35], v[52:55]
	v_mfma_f32_16x16x32_bf16 v[48:51], v[72:75], v[40:43], v[48:51]
	s_waitcnt lgkmcnt(7)
	v_mfma_f32_16x16x32_bf16 v[52:55], v[88:91], v[40:43], v[52:55]
	v_mfma_f32_16x16x32_bf16 v[48:51], v[76:79], v[44:47], v[48:51]
	s_waitcnt lgkmcnt(6)
	v_mfma_f32_16x16x32_bf16 v[52:55], v[92:95], v[44:47], v[52:55]
	s_add_u32 m0, m0, 0x2000
	s_nop 0
	global_load_lds_dwordx4 v236, s[40:41]
	ds_read_b128 v[64:67], v229 offset:8192
	ds_read_b128 v[68:71], v230 offset:8192
	ds_read_b128 v[72:75], v231 offset:8192
	ds_read_b128 v[76:79], v232 offset:8192
	ds_read_b128 v[80:83], v229 offset:12288
	ds_read_b128 v[84:87], v230 offset:12288
	ds_read_b128 v[88:91], v231 offset:12288
	global_load_dwordx2 v[148:149], v171, s[40:41]
	ds_read_b128 v[92:95], v232 offset:12288
	ds_read_b64_tr_b16 v[60:61], v218 offset:35328
	s_waitcnt lgkmcnt(11)
; __device__ __forceinline__ void phase_ssd(const Params& P, int seg, unsigned char* smem) {
;     ...
;               for (int i = 0; i < 2; ++i) { const int q = tid + 512 * i, l = q >> 4, c8 = q & 15; *(v4u*)(sb + T_CS + l * 272 + c8 * 16) = R.Cr[i]; *(v4u*)(sb + T_BS + l * 272 + c8 * 16) = R.Br[i]; }
;               const int l = tid >> 3, p4 = (tid & 7) * 4;
;               const float x0 = bflo(R.Xr.x) * R.dtl, x1 = bfhi(R.Xr.x) * R.dtl, x2 = bflo(R.Xr.y) * R.dtl, x3 = bfhi(R.Xr.y) * R.dtl;
;               v2u d; d.x = cvt_pk_bf16(x0, x1); d.y = cvt_pk_bf16(x2, x3); *(v2u*)(sb + T_XD + l * 80 + p4 * 2) = d;
;               v2u e; e.x = cvt_pk_bf16(x0 * e2, x1 * e2); e.y = cvt_pk_bf16(x2 * e2, x3 * e2); *(v2u*)(sb + T_XE + l * 80 + p4 * 2) = e;
;               *(v2u*)(sb + T_XS + l * 64 + p4 * 2) = R.Xr; *(v2u*)(sb + T_ZS + l * 64 + p4 * 2) = R.Zr;
;               if (w == 0) acP[lane] = R.aclane; }
;             BAR_LDS();
;             if (ci + 2 < nchunks) load_chunk(ci + 2, R);
;             bf16x8 cf[4];
; #pragma unroll
;             for (int k = 0; k < 4; ++k) cf[k] = *(const bf16x8*)(sb + T_CS + (lt * 16 + fr) * 272 + (k * 32 + fq * 8) * 2);
;             f32x4 yo = {0.f, 0.f, 0.f, 0.f};
; #pragma unroll
;             for (int k = 0; k < 4; ++k) { const bf16x8 bb = *(const bf16x8*)((const unsigned char*)StR + (pt * 16 + fr) * 272 + (k * 32 + fq * 8) * 2); yo = mfma16(cf[k], bb, yo); }
; { const f32x4 a4 = *(const f32x4*)(acP + lt * 16 + fq * 4);
; #pragma unroll
;               for (int j = 0; j < 4; ++j) yo[j] *= __expf(a4[j]); }
;             const float acl_fr = acP[lt * 16 + fr]; const int lrow = lt * 16 + fr;
; #pragma unroll
;             for (int t = 0; t < 2; ++t) {
;                 if (2 * t <= lt) {
;                     v2u xb0, xb1;
;                     { const unsigned a0 = lds0 + par * T_BUF + T_XD + (32 * t + 4 * fq + tq) * 80 + (pt * 16 + 4 * tp) * 2, a1 = a0 + 16 * 80; TR_ISSUE(xb0, a0); TR_ISSUE(xb1, a1); }
;                     float m[8];
;                     { f32x4 s0 = {0.f, 0.f, 0.f, 0.f}, s1 = {0.f, 0.f, 0.f, 0.f};
; #pragma unroll
;                       for (int k = 0; k < 4; ++k) { const bf16x8 bf0 = *(const bf16x8*)(sb + T_BS + ((2 * t) * 16 + fr) * 272 + (k * 32 + fq * 8) * 2), bf1 = *(const bf16x8*)(sb + T_BS + ((2 * t + 1) * 16 + fr) * 272 + (k * 32 + fq * 8) * 2);
	ds_read_b64_tr_b16 v[62:63], v218 offset:36608
	v_exp_f32_e32 v168, v167
	s_nop 0
	v_mul_f32_e32 v24, v24, v168
	v_mul_f32_e32 v25, v25, v168
	v_mul_f32_e32 v26, v26, v168
	global_load_dwordx2 v[150:151], v174, s[42:43] nt
	v_mul_f32_e32 v27, v27, v168
	v_lshlrev_b32_e32 v112, 16, v126
	v_and_b32_e32 v113, 0xffff0000, v126
	v_lshlrev_b32_e32 v114, 16, v127
	v_and_b32_e32 v115, 0xffff0000, v127
	v_mul_f32_e32 v120, 0xbfb8aa3b, v112
	v_mul_f32_e32 v121, 0xbfb8aa3b, v113
	global_load_dword v118, v192, s[44:45]
	v_mul_f32_e32 v122, 0xbfb8aa3b, v114
	v_mul_f32_e32 v123, 0xbfb8aa3b, v115
	v_exp_f32_e32 v120, v120
	v_exp_f32_e32 v121, v121
	v_exp_f32_e32 v122, v122
	v_exp_f32_e32 v123, v123
	v_add_f32_e32 v120, 1.0, v120
	global_load_dword v152, v192, s[46:47]
	v_add_f32_e32 v121, 1.0, v121
	v_add_f32_e32 v122, 1.0, v122
	v_add_f32_e32 v123, 1.0, v123
	v_rcp_f32_e32 v120, v120
	v_rcp_f32_e32 v121, v121
	v_rcp_f32_e32 v122, v122
	v_rcp_f32_e32 v123, v123
	global_load_dword v153, v193, s[46:47]
	v_mul_f32_e32 v112, v120, v112
	v_mul_f32_e32 v113, v121, v113
	v_mul_f32_e32 v114, v122, v114
	v_mul_f32_e32 v115, v123, v115
	v_lshlrev_b32_e32 v120, 16, v124
	v_and_b32_e32 v121, 0xffff0000, v124
	s_add_u32 s66, s54, 3
	s_cmp_lt_u32 s66, s39
	s_cselect_b32 s74, 0xc0000, 0
	s_cselect_b32 s75, 0x280000, 0
	s_cselect_b32 s76, 0x4000, 0
	s_add_u32 s40, s40, s74
	s_addc_u32 s41, s41, 0
	s_add_u32 s42, s42, s75
	s_addc_u32 s43, s43, 0
	s_add_u32 s44, s44, s76
	s_addc_u32 s45, s45, 0
	s_add_u32 s46, s46, s76
	s_addc_u32 s47, s47, 0
	v_lshlrev_b32_e32 v122, 16, v125
	v_and_b32_e32 v123, 0xffff0000, v125
	v_sub_f32_e32 v156, v167, v96
	s_waitcnt vmcnt(10)
	v_sub_f32_e32 v157, v167, v97
	v_sub_f32_e32 v158, v167, v98
	ds_write_b128 v196, v[132:135]
	v_sub_f32_e32 v159, v167, v99
	v_exp_f32_e32 v156, v156
	ds_write_b128 v196, v[136:139] offset:8192
	v_exp_f32_e32 v157, v157
	v_exp_f32_e32 v158, v158
	v_exp_f32_e32 v159, v159
	v_sub_f32_e32 v188, v117, v116
	v_mul_f32_e32 v156, v48, v156
	v_mul_f32_e32 v157, v49, v157
	v_mul_f32_e32 v188, 0x3fb8aa3b, v188
	v_mul_f32_e32 v158, v50, v158
	v_mul_f32_e32 v159, v51, v159
	v_exp_f32_e32 v188, v188
	v_sub_f32_e32 v160, v167, v100
	v_sub_f32_e32 v161, v167, v101
	v_lshlrev_b32_e32 v184, 16, v4
	v_sub_f32_e32 v162, v167, v102
	v_sub_f32_e32 v163, v167, v103
	v_exp_f32_e32 v160, v160
	v_and_b32_e32 v185, 0xffff0000, v4
	v_exp_f32_e32 v161, v161
	v_exp_f32_e32 v162, v162
	v_lshlrev_b32_e32 v186, 16, v5
	v_exp_f32_e32 v163, v163
	v_mul_f32_e32 v160, v52, v160
	v_and_b32_e32 v187, 0xffff0000, v5
	v_mul_f32_e32 v161, v53, v161
	v_mul_f32_e32 v162, v54, v162
	v_mul_f32_e32 v163, v55, v163
	v_mul_f32_e32 v184, v184, v6
	v_cvt_pk_bf16_f32 v128, v156, v157
	v_cvt_pk_bf16_f32 v129, v158, v159
	v_mul_f32_e32 v185, v185, v6
	v_cvt_pk_bf16_f32 v130, v160, v161
	v_cvt_pk_bf16_f32 v131, v162, v163
	v_mul_f32_e32 v186, v186, v6
	s_waitcnt lgkmcnt(12)
	v_mfma_f32_16x16x32_bf16 v[24:27], v[56:59], v[128:131], v[24:27]
	ds_read_b128 v[96:99], v216 offset:384
	ds_read_b128 v[100:103], v216 offset:448
	v_mul_f32_e32 v187, v187, v6
	s_waitcnt lgkmcnt(13)
	v_mfma_f32_16x16x32_bf16 v[48:51], v[64:67], v[28:31], 0
	s_waitcnt lgkmcnt(9)
	v_mfma_f32_16x16x32_bf16 v[52:55], v[80:83], v[28:31], 0
	v_cvt_pk_bf16_f32 v190, v184, v185
	v_mfma_f32_16x16x32_bf16 v[48:51], v[68:71], v[32:35], v[48:51]
	s_waitcnt lgkmcnt(8)
	v_mfma_f32_16x16x32_bf16 v[52:55], v[84:87], v[32:35], v[52:55]
	v_cvt_pk_bf16_f32 v191, v186, v187
	v_mfma_f32_16x16x32_bf16 v[48:51], v[72:75], v[40:43], v[48:51]
	s_waitcnt lgkmcnt(7)
	v_mfma_f32_16x16x32_bf16 v[52:55], v[88:91], v[40:43], v[52:55]
	ds_write_b64 v198, v[190:191] offset:32768
	v_mfma_f32_16x16x32_bf16 v[48:51], v[76:79], v[44:47], v[48:51]
	s_waitcnt lgkmcnt(7)
	v_mfma_f32_16x16x32_bf16 v[52:55], v[92:95], v[44:47], v[52:55]
	s_waitcnt lgkmcnt(2)
	v_sub_f32_e32 v156, v167, v96
	v_mul_f32_e32 v184, v184, v188
	v_sub_f32_e32 v157, v167, v97
	v_sub_f32_e32 v158, v167, v98
	v_mul_f32_e32 v185, v185, v188
	v_sub_f32_e32 v159, v167, v99
	v_exp_f32_e32 v156, v156
	v_mul_f32_e32 v186, v186, v188
	v_exp_f32_e32 v157, v157
	v_exp_f32_e32 v158, v158
	v_exp_f32_e32 v159, v159
	v_mul_f32_e32 v187, v187, v188
	v_mul_f32_e32 v156, v48, v156
	v_mul_f32_e32 v157, v49, v157
	v_cvt_pk_bf16_f32 v164, v184, v185
	v_mul_f32_e32 v158, v50, v158
	v_mul_f32_e32 v159, v51, v159
	v_cvt_pk_bf16_f32 v165, v186, v187
	s_waitcnt lgkmcnt(1)
	v_sub_f32_e32 v160, v167, v100
	v_sub_f32_e32 v161, v167, v101
	ds_write_b64 v198, v[164:165] offset:37888
	v_sub_f32_e32 v162, v167, v102
	v_sub_f32_e32 v163, v167, v103
	v_exp_f32_e32 v160, v160
	ds_write_b64 v200, v[4:5] offset:43008
	v_exp_f32_e32 v161, v161
	v_exp_f32_e32 v162, v162
	ds_write_b64 v200, v[36:37] offset:47616
	v_exp_f32_e32 v163, v163
	v_mul_f32_e32 v160, v52, v160
	v_mul_f32_e32 v189, 0x3fb8aa3b, v116
	v_mul_f32_e32 v161, v53, v161
	v_mul_f32_e32 v162, v54, v162
	v_mul_f32_e32 v163, v55, v163
	ds_write_b32 v202, v189
	v_cndmask_b32_e64 v160, 0, v160, s[14:15]
	v_cndmask_b32_e64 v161, 0, v161, s[16:17]
	v_mul_f32_e32 v166, 0x3fb8aa3b, v117
	v_cndmask_b32_e64 v162, 0, v162, s[22:23]
	v_cndmask_b32_e64 v163, 0, v163, s[34:35]
	v_exp_f32_e32 v166, v166
	v_cvt_pk_bf16_f32 v128, v156, v157
	v_cvt_pk_bf16_f32 v129, v158, v159
	v_cvt_pk_bf16_f32 v130, v160, v161
	v_cvt_pk_bf16_f32 v131, v162, v163
	s_nop 1
	v_mfma_f32_16x16x32_bf16 v[24:27], v[60:63], v[128:131], v[24:27]
	s_mul_i32 s65, s56, 0x2000
	s_add_u32 s65, s65, 0x304f1000
	s_add_u32 s48, s0, s65
	s_addc_u32 s49, s1, 0
	s_nop 3
	v_fma_f32 v156, s61, v120, v24
	v_fma_f32 v157, s61, v121, v25
	v_fma_f32 v158, s61, v122, v26
	v_fma_f32 v159, s61, v123, v27
	v_mul_f32_e32 v156, v156, v112
	v_mul_f32_e32 v157, v157, v113
	v_mul_f32_e32 v158, v158, v114
	v_mul_f32_e32 v159, v159, v115
	v_cvt_pk_bf16_f32 v154, v156, v157
	v_cvt_pk_bf16_f32 v155, v158, v159
	global_store_dwordx2 v194, v[154:155], s[48:49]
	s_add_u32 s65, s54, 1
	s_sub_u32 s65, s65, s60
	s_lshl_b32 s65, s65, 6
	s_add_u32 s56, s65, s20
	s_waitcnt lgkmcnt(0)
	s_barrier
	s_mov_b32 s80, s77
	s_mov_b32 s77, s78
	s_mov_b32 s78, s79
	s_mov_b32 s79, s80
	s_add_u32 s54, s54, 1
	s_cmp_lt_u32 s54, s39
	s_cbranch_scc1 .Lssd_loop3
.Lssd_done:
	s_cmp_eq_u32 s24, 3
	s_cbranch_scc1 .Lssd_nostore
	s_cmp_ge_u32 s55, 2
	s_cbranch_scc1 .Lssd_nostore
	s_nop 7
	v_add_u32_e32 v157, 0x2000, v195
	global_store_dwordx4 v195, v[8:11], s[50:51]
	global_store_dwordx4 v157, v[12:15], s[50:51]
	global_store_dwordx4 v195, v[16:19], s[50:51] offset:64
	global_store_dwordx4 v157, v[20:23], s[50:51] offset:64
.Lssd_nostore:
	s_waitcnt vmcnt(0)
	s_barrier
	s_add_u32 s18, s18, s63
	s_cmp_lt_u32 s18, 256
	s_cbranch_scc1 .Lssd_item
